# speedup vs baseline: 1.0070x; 1.0070x over previous
; DI unsigned pk_f16(float lo, float hi) { f32x2_t v = {lo, hi}; return __builtin_bit_cast(unsigned, __builtin_convertvector(v, f16x2_t)); }
; DI float bflo(unsigned u) { return __uint_as_float(u << 16); }
; DI float bfhi(unsigned u) { return __uint_as_float(u & 0xffff0000u); }
; #define EPI_M _Pragma("unroll") for (int m = 0; m < 8; ++m)
; #define EPI_N _Pragma("unroll") for (int n = 0; n < 4; ++n)
; DI void p5_phase(const Params& p, char* lds) {
;     ...
;     EPI_IDX_N
;     {
;       u32x2 gq[2][4];
;       EPI_N gq[0][n] = tg[(0 * 4 + n) * 512 + tid];
;       EPI_M {
;         if (m < 7) EPI_N gq[(m + 1) & 1][n] = tg[((m + 1) * 4 + n) * 512 + tid];
;         EPI_N {
;           const u32x2 g = gq[m & 1][n];
;           u32x2 o; o[0] = pk_f16(ACC(m, n)[0] * bflo(g[0]), ACC(m, n)[1] * bfhi(g[0])); o[1] = pk_f16(ACC(m, n)[2] * bflo(g[1]), ACC(m, n)[3] * bfhi(g[1]));
;           tr[(m * 4 + n) * 512 + tid] = o;
;         }
;         __builtin_amdgcn_sched_barrier(0);
;       }
;     }
.LBB0_982:
	s_or_b64 exec, exec, s[8:9]
	s_waitcnt vmcnt(0)
	s_barrier
	s_getreg_b32 s2, hwreg(HW_REG_HW_ID, 0, 6)
	s_lshl_b32 s2, s2, 2
	s_and_b32 s2, s2, 0xfc
	s_add_i32 s2, s2, 0x20040
	v_mov_b32_e32 v64, s2
	ds_read_b32 v64, v64
	s_waitcnt lgkmcnt(0)
	v_readfirstlane_b32 s2, v64
	s_nop 1
	v_lshl_or_b32 v130, s2, 6, v214
	s_nop 0
	v_ashrrev_i32_e32 v131, 31, v130
	v_lshlrev_b64 v[162:163], 3, v[130:131]
	v_lshl_add_u64 v[132:133], s[10:11], 0, v[162:163]
	s_add_u32 s100, s10, 0x800
	s_addc_u32 s101, s11, 0
	global_load_dwordx2 v[166:167], v162, s[100:101] offset:-2048
	global_load_dwordx2 v[168:169], v162, s[100:101] offset:2048
	s_add_u32 s100, s100, 0x2000
	s_addc_u32 s101, s101, 0
	global_load_dwordx2 v[170:171], v162, s[100:101] offset:-2048
	global_load_dwordx2 v[172:173], v162, s[100:101] offset:2048
	s_add_u32 s100, s100, 0x2000
	s_addc_u32 s101, s101, 0
	global_load_dwordx2 v[174:175], v162, s[100:101] offset:-2048
	global_load_dwordx2 v[176:177], v162, s[100:101] offset:2048
	s_add_u32 s100, s100, 0x2000
	s_addc_u32 s101, s101, 0
	global_load_dwordx2 v[178:179], v162, s[100:101] offset:-2048
	global_load_dwordx2 v[180:181], v162, s[100:101] offset:2048
	s_add_u32 s100, s100, 0x2000
	s_addc_u32 s101, s101, 0
	global_load_dwordx2 v[182:183], v162, s[100:101] offset:-2048
	global_load_dwordx2 v[184:185], v162, s[100:101] offset:2048
	s_add_u32 s100, s100, 0x2000
	s_addc_u32 s101, s101, 0
	global_load_dwordx2 v[186:187], v162, s[100:101] offset:-2048
	global_load_dwordx2 v[188:189], v162, s[100:101] offset:2048
	s_add_u32 s100, s100, 0x2000
	s_addc_u32 s101, s101, 0
	global_load_dwordx2 v[190:191], v162, s[100:101] offset:-2048
	global_load_dwordx2 v[192:193], v162, s[100:101] offset:2048
	s_add_u32 s100, s100, 0x2000
	s_addc_u32 s101, s101, 0
	global_load_dwordx2 v[194:195], v162, s[100:101] offset:-2048
	global_load_dwordx2 v[196:197], v162, s[100:101] offset:2048
	s_add_u32 s100, s100, 0x2000
	s_addc_u32 s101, s101, 0
	global_load_dwordx2 v[198:199], v162, s[100:101] offset:-2048
	global_load_dwordx2 v[200:201], v162, s[100:101] offset:2048
	s_add_u32 s100, s100, 0x2000
	s_addc_u32 s101, s101, 0
	global_load_dwordx2 v[202:203], v162, s[100:101] offset:-2048
	global_load_dwordx2 v[204:205], v162, s[100:101] offset:2048
	s_add_u32 s100, s100, 0x2000
	s_addc_u32 s101, s101, 0
	global_load_dwordx2 v[206:207], v162, s[100:101] offset:-2048
	global_load_dwordx2 v[208:209], v162, s[100:101] offset:2048
	s_add_u32 s100, s100, 0x2000
	s_addc_u32 s101, s101, 0
	global_load_dwordx2 v[210:211], v162, s[100:101] offset:-2048
	global_load_dwordx2 v[212:213], v162, s[100:101] offset:2048
	s_add_u32 s100, s100, 0x2000
	s_addc_u32 s101, s101, 0
	global_load_dwordx2 v[222:223], v162, s[100:101] offset:-2048
	global_load_dwordx2 v[224:225], v162, s[100:101] offset:2048
	s_add_u32 s100, s100, 0x2000
	s_addc_u32 s101, s101, 0
	global_load_dwordx2 v[226:227], v162, s[100:101] offset:-2048
	global_load_dwordx2 v[228:229], v162, s[100:101] offset:2048
	s_add_u32 s100, s100, 0x2000
	s_addc_u32 s101, s101, 0
	global_load_dwordx2 v[230:231], v162, s[100:101] offset:-2048
	global_load_dwordx2 v[232:233], v162, s[100:101] offset:2048
	s_add_u32 s100, s100, 0x2000
	s_addc_u32 s101, s101, 0
	global_load_dwordx2 v[234:235], v162, s[100:101] offset:-2048
	global_load_dwordx2 v[236:237], v162, s[100:101] offset:2048
	v_add_u32_e32 v132, 0x200, v130
	v_ashrrev_i32_e32 v133, 31, v132
	v_lshlrev_b64 v[156:157], 3, v[132:133]
	v_lshl_add_u64 v[132:133], s[10:11], 0, v[156:157]
	v_add_u32_e32 v132, 0x400, v130
	v_ashrrev_i32_e32 v133, 31, v132
	v_lshlrev_b64 v[152:153], 3, v[132:133]
	v_lshl_add_u64 v[132:133], s[10:11], 0, v[152:153]
	v_add_u32_e32 v132, 0x600, v130
	v_ashrrev_i32_e32 v133, 31, v132
	v_lshlrev_b64 v[154:155], 3, v[132:133]
	v_lshl_add_u64 v[132:133], s[10:11], 0, v[154:155]
	v_add_u32_e32 v132, 0x800, v130
	v_ashrrev_i32_e32 v133, 31, v132
	v_lshlrev_b64 v[132:133], 3, v[132:133]
	v_lshl_add_u64 v[134:135], s[10:11], 0, v[132:133]
	v_add_u32_e32 v134, 0xa00, v130
	v_ashrrev_i32_e32 v135, 31, v134
	v_lshlrev_b64 v[134:135], 3, v[134:135]
	v_lshl_add_u64 v[136:137], s[10:11], 0, v[134:135]
	v_add_u32_e32 v136, 0xc00, v130
	v_ashrrev_i32_e32 v137, 31, v136
	v_lshlrev_b64 v[136:137], 3, v[136:137]
	v_lshl_add_u64 v[144:145], s[10:11], 0, v[136:137]
	v_add_u32_e32 v144, 0xe00, v130
	v_ashrrev_i32_e32 v145, 31, v144
	v_lshlrev_b64 v[148:149], 3, v[144:145]
	v_lshl_add_u64 v[144:145], s[10:11], 0, v[148:149]
	s_waitcnt vmcnt(31)
	v_mov_b32_e32 v142, v166
	v_mov_b32_e32 v143, v167
	v_lshlrev_b32_e32 v144, 16, v142
	v_and_b32_e32 v145, 0xffff0000, v142
	v_lshlrev_b32_e32 v142, 16, v143
	v_and_b32_e32 v143, 0xffff0000, v143
	v_pk_mul_f32 v[126:127], v[126:127], v[144:145]
	v_pk_mul_f32 v[128:129], v[128:129], v[142:143]
	v_cvt_pk_f16_f32 v126, v126, v127
	v_cvt_pk_f16_f32 v127, v128, v129
	v_lshl_add_u64 v[128:129], s[12:13], 0, v[162:163]
	global_store_dwordx2 v[128:129], v[126:127], off
	s_waitcnt vmcnt(31)
	v_mov_b32_e32 v164, v168
	v_mov_b32_e32 v165, v169
	v_lshlrev_b32_e32 v126, 16, v164
	v_and_b32_e32 v127, 0xffff0000, v164
	v_pk_mul_f32 v[122:123], v[122:123], v[126:127]
	v_lshlrev_b32_e32 v126, 16, v165
	v_and_b32_e32 v127, 0xffff0000, v165
	v_pk_mul_f32 v[124:125], v[124:125], v[126:127]
	v_cvt_pk_f16_f32 v122, v122, v123
	v_cvt_pk_f16_f32 v123, v124, v125
	v_lshl_add_u64 v[124:125], s[12:13], 0, v[156:157]
	global_store_dwordx2 v[124:125], v[122:123], off
	s_waitcnt vmcnt(31)
; DI unsigned pk_f16(float lo, float hi) { f32x2_t v = {lo, hi}; return __builtin_bit_cast(unsigned, __builtin_convertvector(v, f16x2_t)); }
; DI float bflo(unsigned u) { return __uint_as_float(u << 16); }
; DI float bfhi(unsigned u) { return __uint_as_float(u & 0xffff0000u); }
; #define EPI_M _Pragma("unroll") for (int m = 0; m < 8; ++m)
; #define EPI_N _Pragma("unroll") for (int n = 0; n < 4; ++n)
; DI void p5_phase(const Params& p, char* lds) {
;     ...
;       EPI_M {
;         if (m < 7) EPI_N gq[(m + 1) & 1][n] = tg[((m + 1) * 4 + n) * 512 + tid];
;         EPI_N {
;           const u32x2 g = gq[m & 1][n];
;           u32x2 o; o[0] = pk_f16(ACC(m, n)[0] * bflo(g[0]), ACC(m, n)[1] * bfhi(g[0])); o[1] = pk_f16(ACC(m, n)[2] * bflo(g[1]), ACC(m, n)[3] * bfhi(g[1]));
;           tr[(m * 4 + n) * 512 + tid] = o;
;         }
;         __builtin_amdgcn_sched_barrier(0);
;       }
	v_mov_b32_e32 v158, v170
	v_mov_b32_e32 v159, v171
	v_lshlrev_b32_e32 v122, 16, v158
	v_and_b32_e32 v123, 0xffff0000, v158
	v_pk_mul_f32 v[118:119], v[118:119], v[122:123]
	v_lshlrev_b32_e32 v122, 16, v159
	v_and_b32_e32 v123, 0xffff0000, v159
	v_pk_mul_f32 v[120:121], v[120:121], v[122:123]
	v_cvt_pk_f16_f32 v118, v118, v119
	v_cvt_pk_f16_f32 v119, v120, v121
	v_lshl_add_u64 v[120:121], s[12:13], 0, v[152:153]
	global_store_dwordx2 v[120:121], v[118:119], off
	s_waitcnt vmcnt(31)
	v_mov_b32_e32 v160, v172
	v_mov_b32_e32 v161, v173
	v_lshlrev_b32_e32 v118, 16, v160
	v_and_b32_e32 v119, 0xffff0000, v160
	v_pk_mul_f32 v[114:115], v[114:115], v[118:119]
	v_lshlrev_b32_e32 v118, 16, v161
	v_and_b32_e32 v119, 0xffff0000, v161
	v_pk_mul_f32 v[116:117], v[116:117], v[118:119]
	v_cvt_pk_f16_f32 v114, v114, v115
	v_cvt_pk_f16_f32 v115, v116, v117
	v_lshl_add_u64 v[116:117], s[12:13], 0, v[154:155]
	global_store_dwordx2 v[116:117], v[114:115], off
	v_add_u32_e32 v114, 0x1000, v130
	v_add_u32_e32 v118, 0x1200, v130
	v_add_u32_e32 v122, 0x1400, v130
	v_add_u32_e32 v126, 0x1600, v130
	v_ashrrev_i32_e32 v115, 31, v114
	v_ashrrev_i32_e32 v119, 31, v118
	v_ashrrev_i32_e32 v123, 31, v122
	v_ashrrev_i32_e32 v127, 31, v126
	v_lshlrev_b64 v[114:115], 3, v[114:115]
	v_lshlrev_b64 v[118:119], 3, v[118:119]
	v_lshlrev_b64 v[122:123], 3, v[122:123]
	v_lshlrev_b64 v[126:127], 3, v[126:127]
	v_lshl_add_u64 v[116:117], s[10:11], 0, v[114:115]
	v_lshl_add_u64 v[120:121], s[10:11], 0, v[118:119]
	v_lshl_add_u64 v[124:125], s[10:11], 0, v[122:123]
	v_lshl_add_u64 v[128:129], s[10:11], 0, v[126:127]
	s_nop 0
	s_nop 0
	s_nop 0
	s_waitcnt vmcnt(31)
	v_mov_b32_e32 v138, v174
	v_mov_b32_e32 v139, v175
	v_lshlrev_b32_e32 v142, 16, v138
	v_and_b32_e32 v143, 0xffff0000, v138
	v_lshlrev_b32_e32 v138, 16, v139
	v_and_b32_e32 v139, 0xffff0000, v139
	v_pk_mul_f32 v[110:111], v[110:111], v[142:143]
	v_pk_mul_f32 v[112:113], v[112:113], v[138:139]
	v_cvt_pk_f16_f32 v110, v110, v111
	v_cvt_pk_f16_f32 v111, v112, v113
	v_lshl_add_u64 v[112:113], s[12:13], 0, v[132:133]
	global_store_dwordx2 v[112:113], v[110:111], off
	s_waitcnt vmcnt(31)
	v_mov_b32_e32 v140, v176
	v_mov_b32_e32 v141, v177
	v_lshlrev_b32_e32 v110, 16, v140
	v_and_b32_e32 v111, 0xffff0000, v140
	v_pk_mul_f32 v[102:103], v[102:103], v[110:111]
	v_lshlrev_b32_e32 v110, 16, v141
	v_and_b32_e32 v111, 0xffff0000, v141
	v_pk_mul_f32 v[104:105], v[104:105], v[110:111]
	v_cvt_pk_f16_f32 v102, v102, v103
	v_cvt_pk_f16_f32 v103, v104, v105
	v_lshl_add_u64 v[104:105], s[12:13], 0, v[134:135]
	global_store_dwordx2 v[104:105], v[102:103], off
	s_waitcnt vmcnt(31)
	v_mov_b32_e32 v146, v178
	v_mov_b32_e32 v147, v179
	v_lshlrev_b32_e32 v102, 16, v146
	v_and_b32_e32 v103, 0xffff0000, v146
	v_lshlrev_b32_e32 v104, 16, v147
	v_and_b32_e32 v105, 0xffff0000, v147
	v_pk_mul_f32 v[102:103], v[106:107], v[102:103]
	v_pk_mul_f32 v[104:105], v[108:109], v[104:105]
	v_cvt_pk_f16_f32 v102, v102, v103
	v_cvt_pk_f16_f32 v103, v104, v105
	v_lshl_add_u64 v[104:105], s[12:13], 0, v[136:137]
	global_store_dwordx2 v[104:105], v[102:103], off
	s_waitcnt vmcnt(31)
	v_mov_b32_e32 v150, v180
	v_mov_b32_e32 v151, v181
	v_lshlrev_b32_e32 v102, 16, v150
	v_and_b32_e32 v103, 0xffff0000, v150
	v_pk_mul_f32 v[98:99], v[98:99], v[102:103]
	v_lshlrev_b32_e32 v102, 16, v151
	v_and_b32_e32 v103, 0xffff0000, v151
	v_pk_mul_f32 v[100:101], v[100:101], v[102:103]
	v_cvt_pk_f16_f32 v98, v98, v99
	v_cvt_pk_f16_f32 v99, v100, v101
	v_lshl_add_u64 v[100:101], s[12:13], 0, v[148:149]
	global_store_dwordx2 v[100:101], v[98:99], off
	v_add_u32_e32 v98, 0x1800, v130
	v_add_u32_e32 v102, 0x1a00, v130
	v_add_u32_e32 v106, 0x1c00, v130
	v_add_u32_e32 v110, 0x1e00, v130
	v_ashrrev_i32_e32 v99, 31, v98
	v_ashrrev_i32_e32 v103, 31, v102
	v_ashrrev_i32_e32 v107, 31, v106
	v_ashrrev_i32_e32 v111, 31, v110
	v_lshlrev_b64 v[98:99], 3, v[98:99]
	v_lshlrev_b64 v[102:103], 3, v[102:103]
	v_lshlrev_b64 v[106:107], 3, v[106:107]
	v_lshlrev_b64 v[110:111], 3, v[110:111]
	v_lshl_add_u64 v[100:101], s[10:11], 0, v[98:99]
	v_lshl_add_u64 v[104:105], s[10:11], 0, v[102:103]
	v_lshl_add_u64 v[108:109], s[10:11], 0, v[106:107]
	v_lshl_add_u64 v[112:113], s[10:11], 0, v[110:111]
	s_nop 0
	s_nop 0
	s_nop 0
	s_waitcnt vmcnt(31)
	v_mov_b32_e32 v116, v182
	v_mov_b32_e32 v117, v183
	v_lshlrev_b32_e32 v132, 16, v116
	v_and_b32_e32 v133, 0xffff0000, v116
	v_lshlrev_b32_e32 v116, 16, v117
	v_and_b32_e32 v117, 0xffff0000, v117
	v_pk_mul_f32 v[94:95], v[94:95], v[132:133]
	v_pk_mul_f32 v[96:97], v[96:97], v[116:117]
	v_cvt_pk_f16_f32 v94, v94, v95
	v_cvt_pk_f16_f32 v95, v96, v97
	v_lshl_add_u64 v[96:97], s[12:13], 0, v[114:115]
	global_store_dwordx2 v[96:97], v[94:95], off
	s_waitcnt vmcnt(31)
	v_mov_b32_e32 v120, v184
	v_mov_b32_e32 v121, v185
	v_lshlrev_b32_e32 v94, 16, v120
	v_and_b32_e32 v95, 0xffff0000, v120
	v_pk_mul_f32 v[86:87], v[86:87], v[94:95]
	v_lshlrev_b32_e32 v94, 16, v121
	v_and_b32_e32 v95, 0xffff0000, v121
	v_pk_mul_f32 v[88:89], v[88:89], v[94:95]
	v_cvt_pk_f16_f32 v86, v86, v87
	v_cvt_pk_f16_f32 v87, v88, v89
	v_lshl_add_u64 v[88:89], s[12:13], 0, v[118:119]
	global_store_dwordx2 v[88:89], v[86:87], off
	s_waitcnt vmcnt(31)
	v_mov_b32_e32 v124, v186
	v_mov_b32_e32 v125, v187
	v_lshlrev_b32_e32 v86, 16, v124
	v_and_b32_e32 v87, 0xffff0000, v124
	v_lshlrev_b32_e32 v88, 16, v125
	v_and_b32_e32 v89, 0xffff0000, v125
	v_pk_mul_f32 v[86:87], v[90:91], v[86:87]
	v_pk_mul_f32 v[88:89], v[92:93], v[88:89]
	v_cvt_pk_f16_f32 v86, v86, v87
	v_cvt_pk_f16_f32 v87, v88, v89
	v_lshl_add_u64 v[88:89], s[12:13], 0, v[122:123]
	global_store_dwordx2 v[88:89], v[86:87], off
	s_waitcnt vmcnt(31)
; DI unsigned pk_f16(float lo, float hi) { f32x2_t v = {lo, hi}; return __builtin_bit_cast(unsigned, __builtin_convertvector(v, f16x2_t)); }
; DI float bflo(unsigned u) { return __uint_as_float(u << 16); }
; DI float bfhi(unsigned u) { return __uint_as_float(u & 0xffff0000u); }
; #define EPI_M _Pragma("unroll") for (int m = 0; m < 8; ++m)
; #define EPI_N _Pragma("unroll") for (int n = 0; n < 4; ++n)
; DI void p5_phase(const Params& p, char* lds) {
;     ...
;       EPI_M {
;         if (m < 7) EPI_N gq[(m + 1) & 1][n] = tg[((m + 1) * 4 + n) * 512 + tid];
;         EPI_N {
;           const u32x2 g = gq[m & 1][n];
;           u32x2 o; o[0] = pk_f16(ACC(m, n)[0] * bflo(g[0]), ACC(m, n)[1] * bfhi(g[0])); o[1] = pk_f16(ACC(m, n)[2] * bflo(g[1]), ACC(m, n)[3] * bfhi(g[1]));
;           tr[(m * 4 + n) * 512 + tid] = o;
;         }
;         __builtin_amdgcn_sched_barrier(0);
;       }
	v_mov_b32_e32 v128, v188
	v_mov_b32_e32 v129, v189
	v_lshlrev_b32_e32 v86, 16, v128
	v_and_b32_e32 v87, 0xffff0000, v128
	v_pk_mul_f32 v[82:83], v[82:83], v[86:87]
	v_lshlrev_b32_e32 v86, 16, v129
	v_and_b32_e32 v87, 0xffff0000, v129
	v_pk_mul_f32 v[84:85], v[84:85], v[86:87]
	v_cvt_pk_f16_f32 v82, v82, v83
	v_cvt_pk_f16_f32 v83, v84, v85
	v_lshl_add_u64 v[84:85], s[12:13], 0, v[126:127]
	global_store_dwordx2 v[84:85], v[82:83], off
	v_add_u32_e32 v82, 0x2000, v130
	v_add_u32_e32 v86, 0x2200, v130
	v_add_u32_e32 v90, 0x2400, v130
	v_add_u32_e32 v94, 0x2600, v130
	v_ashrrev_i32_e32 v83, 31, v82
	v_ashrrev_i32_e32 v87, 31, v86
	v_ashrrev_i32_e32 v91, 31, v90
	v_ashrrev_i32_e32 v95, 31, v94
	v_lshlrev_b64 v[82:83], 3, v[82:83]
	v_lshlrev_b64 v[86:87], 3, v[86:87]
	v_lshlrev_b64 v[90:91], 3, v[90:91]
	v_lshlrev_b64 v[94:95], 3, v[94:95]
	v_lshl_add_u64 v[84:85], s[10:11], 0, v[82:83]
	v_lshl_add_u64 v[88:89], s[10:11], 0, v[86:87]
	v_lshl_add_u64 v[92:93], s[10:11], 0, v[90:91]
	v_lshl_add_u64 v[96:97], s[10:11], 0, v[94:95]
	s_nop 0
	s_nop 0
	s_nop 0
	s_waitcnt vmcnt(31)
	v_mov_b32_e32 v100, v190
	v_mov_b32_e32 v101, v191
	v_lshlrev_b32_e32 v114, 16, v100
	v_and_b32_e32 v115, 0xffff0000, v100
	v_lshlrev_b32_e32 v100, 16, v101
	v_and_b32_e32 v101, 0xffff0000, v101
	v_pk_mul_f32 v[78:79], v[78:79], v[114:115]
	v_pk_mul_f32 v[80:81], v[80:81], v[100:101]
	v_cvt_pk_f16_f32 v78, v78, v79
	v_cvt_pk_f16_f32 v79, v80, v81
	v_lshl_add_u64 v[80:81], s[12:13], 0, v[98:99]
	global_store_dwordx2 v[80:81], v[78:79], off
	s_waitcnt vmcnt(31)
	v_mov_b32_e32 v104, v192
	v_mov_b32_e32 v105, v193
	v_lshlrev_b32_e32 v78, 16, v104
	v_and_b32_e32 v79, 0xffff0000, v104
	v_pk_mul_f32 v[70:71], v[70:71], v[78:79]
	v_lshlrev_b32_e32 v78, 16, v105
	v_and_b32_e32 v79, 0xffff0000, v105
	v_pk_mul_f32 v[72:73], v[72:73], v[78:79]
	v_cvt_pk_f16_f32 v70, v70, v71
	v_cvt_pk_f16_f32 v71, v72, v73
	v_lshl_add_u64 v[72:73], s[12:13], 0, v[102:103]
	global_store_dwordx2 v[72:73], v[70:71], off
	s_waitcnt vmcnt(31)
	v_mov_b32_e32 v108, v194
	v_mov_b32_e32 v109, v195
	v_lshlrev_b32_e32 v70, 16, v108
	v_and_b32_e32 v71, 0xffff0000, v108
	v_lshlrev_b32_e32 v72, 16, v109
	v_and_b32_e32 v73, 0xffff0000, v109
	v_pk_mul_f32 v[70:71], v[74:75], v[70:71]
	v_pk_mul_f32 v[72:73], v[76:77], v[72:73]
	v_cvt_pk_f16_f32 v70, v70, v71
	v_cvt_pk_f16_f32 v71, v72, v73
	v_lshl_add_u64 v[72:73], s[12:13], 0, v[106:107]
	global_store_dwordx2 v[72:73], v[70:71], off
	s_waitcnt vmcnt(31)
	v_mov_b32_e32 v112, v196
	v_mov_b32_e32 v113, v197
	v_lshlrev_b32_e32 v70, 16, v112
	v_and_b32_e32 v71, 0xffff0000, v112
	v_pk_mul_f32 v[66:67], v[66:67], v[70:71]
	v_lshlrev_b32_e32 v70, 16, v113
	v_and_b32_e32 v71, 0xffff0000, v113
	v_pk_mul_f32 v[68:69], v[68:69], v[70:71]
	v_cvt_pk_f16_f32 v66, v66, v67
	v_cvt_pk_f16_f32 v67, v68, v69
	v_lshl_add_u64 v[68:69], s[12:13], 0, v[110:111]
	global_store_dwordx2 v[68:69], v[66:67], off
	v_add_u32_e32 v66, 0x2800, v130
	v_add_u32_e32 v70, 0x2a00, v130
	v_add_u32_e32 v74, 0x2c00, v130
	v_add_u32_e32 v78, 0x2e00, v130
	v_ashrrev_i32_e32 v67, 31, v66
	v_ashrrev_i32_e32 v71, 31, v70
	v_ashrrev_i32_e32 v75, 31, v74
	v_ashrrev_i32_e32 v79, 31, v78
	v_lshlrev_b64 v[66:67], 3, v[66:67]
	v_lshlrev_b64 v[70:71], 3, v[70:71]
	v_lshlrev_b64 v[74:75], 3, v[74:75]
	v_lshlrev_b64 v[78:79], 3, v[78:79]
	v_lshl_add_u64 v[68:69], s[10:11], 0, v[66:67]
	v_lshl_add_u64 v[72:73], s[10:11], 0, v[70:71]
	v_lshl_add_u64 v[76:77], s[10:11], 0, v[74:75]
	v_lshl_add_u64 v[80:81], s[10:11], 0, v[78:79]
	s_nop 0
	s_nop 0
	s_nop 0
	s_waitcnt vmcnt(31)
	v_mov_b32_e32 v84, v198
	v_mov_b32_e32 v85, v199
	v_lshlrev_b32_e32 v98, 16, v84
	v_and_b32_e32 v99, 0xffff0000, v84
	v_lshlrev_b32_e32 v84, 16, v85
	v_and_b32_e32 v85, 0xffff0000, v85
	v_pk_mul_f32 v[60:61], v[60:61], v[98:99]
	v_pk_mul_f32 v[62:63], v[62:63], v[84:85]
	v_cvt_pk_f16_f32 v60, v60, v61
	v_cvt_pk_f16_f32 v61, v62, v63
	v_lshl_add_u64 v[62:63], s[12:13], 0, v[82:83]
	global_store_dwordx2 v[62:63], v[60:61], off
	s_waitcnt vmcnt(31)
	v_mov_b32_e32 v88, v200
	v_mov_b32_e32 v89, v201
	v_lshlrev_b32_e32 v60, 16, v88
	v_and_b32_e32 v61, 0xffff0000, v88
	v_pk_mul_f32 v[56:57], v[56:57], v[60:61]
	v_lshlrev_b32_e32 v60, 16, v89
	v_and_b32_e32 v61, 0xffff0000, v89
	v_pk_mul_f32 v[58:59], v[58:59], v[60:61]
	v_cvt_pk_f16_f32 v56, v56, v57
	v_cvt_pk_f16_f32 v57, v58, v59
	v_lshl_add_u64 v[58:59], s[12:13], 0, v[86:87]
	global_store_dwordx2 v[58:59], v[56:57], off
	s_waitcnt vmcnt(31)
	v_mov_b32_e32 v92, v202
	v_mov_b32_e32 v93, v203
	v_lshlrev_b32_e32 v56, 16, v92
	v_and_b32_e32 v57, 0xffff0000, v92
	v_pk_mul_f32 v[52:53], v[52:53], v[56:57]
	v_lshlrev_b32_e32 v56, 16, v93
	v_and_b32_e32 v57, 0xffff0000, v93
	v_pk_mul_f32 v[54:55], v[54:55], v[56:57]
	v_cvt_pk_f16_f32 v52, v52, v53
	v_cvt_pk_f16_f32 v53, v54, v55
	v_lshl_add_u64 v[54:55], s[12:13], 0, v[90:91]
	global_store_dwordx2 v[54:55], v[52:53], off
	s_waitcnt vmcnt(31)
	v_mov_b32_e32 v96, v204
	v_mov_b32_e32 v97, v205
	v_lshlrev_b32_e32 v52, 16, v96
	v_and_b32_e32 v53, 0xffff0000, v96
	v_pk_mul_f32 v[48:49], v[48:49], v[52:53]
	v_lshlrev_b32_e32 v52, 16, v97
	v_and_b32_e32 v53, 0xffff0000, v97
	v_pk_mul_f32 v[50:51], v[50:51], v[52:53]
	v_cvt_pk_f16_f32 v48, v48, v49
	v_cvt_pk_f16_f32 v49, v50, v51
	v_lshl_add_u64 v[50:51], s[12:13], 0, v[94:95]
	global_store_dwordx2 v[50:51], v[48:49], off
	v_add_u32_e32 v48, 0x3000, v130
	v_add_u32_e32 v52, 0x3200, v130
	v_add_u32_e32 v56, 0x3400, v130
	v_add_u32_e32 v60, 0x3600, v130
	v_ashrrev_i32_e32 v49, 31, v48
	v_ashrrev_i32_e32 v53, 31, v52
	v_ashrrev_i32_e32 v57, 31, v56
	v_ashrrev_i32_e32 v61, 31, v60
	v_lshlrev_b64 v[48:49], 3, v[48:49]
	v_lshlrev_b64 v[52:53], 3, v[52:53]
	v_lshlrev_b64 v[56:57], 3, v[56:57]
	v_lshlrev_b64 v[60:61], 3, v[60:61]
	v_lshl_add_u64 v[50:51], s[10:11], 0, v[48:49]
	v_lshl_add_u64 v[54:55], s[10:11], 0, v[52:53]
	v_lshl_add_u64 v[58:59], s[10:11], 0, v[56:57]
	v_lshl_add_u64 v[62:63], s[10:11], 0, v[60:61]
	s_nop 0
	s_nop 0
	s_nop 0
	s_waitcnt vmcnt(31)
; DI unsigned pk_f16(float lo, float hi) { f32x2_t v = {lo, hi}; return __builtin_bit_cast(unsigned, __builtin_convertvector(v, f16x2_t)); }
; DI float bflo(unsigned u) { return __uint_as_float(u << 16); }
; DI float bfhi(unsigned u) { return __uint_as_float(u & 0xffff0000u); }
; #define EPI_M _Pragma("unroll") for (int m = 0; m < 8; ++m)
; #define EPI_N _Pragma("unroll") for (int n = 0; n < 4; ++n)
; DI void p5_phase(const Params& p, char* lds) {
;     ...
;       EPI_M {
;         if (m < 7) EPI_N gq[(m + 1) & 1][n] = tg[((m + 1) * 4 + n) * 512 + tid];
;         EPI_N {
;           const u32x2 g = gq[m & 1][n];
;           u32x2 o; o[0] = pk_f16(ACC(m, n)[0] * bflo(g[0]), ACC(m, n)[1] * bfhi(g[0])); o[1] = pk_f16(ACC(m, n)[2] * bflo(g[1]), ACC(m, n)[3] * bfhi(g[1]));
;           tr[(m * 4 + n) * 512 + tid] = o;
;         }
;         __builtin_amdgcn_sched_barrier(0);
;       }
	v_mov_b32_e32 v68, v206
	v_mov_b32_e32 v69, v207
	v_lshlrev_b32_e32 v82, 16, v68
	v_and_b32_e32 v83, 0xffff0000, v68
	v_lshlrev_b32_e32 v68, 16, v69
	v_and_b32_e32 v69, 0xffff0000, v69
	v_pk_mul_f32 v[44:45], v[44:45], v[82:83]
	v_pk_mul_f32 v[46:47], v[46:47], v[68:69]
	v_cvt_pk_f16_f32 v44, v44, v45
	v_cvt_pk_f16_f32 v45, v46, v47
	v_lshl_add_u64 v[46:47], s[12:13], 0, v[66:67]
	global_store_dwordx2 v[46:47], v[44:45], off
	s_waitcnt vmcnt(31)
	v_mov_b32_e32 v72, v208
	v_mov_b32_e32 v73, v209
	v_lshlrev_b32_e32 v44, 16, v72
	v_and_b32_e32 v45, 0xffff0000, v72
	v_pk_mul_f32 v[40:41], v[40:41], v[44:45]
	v_lshlrev_b32_e32 v44, 16, v73
	v_and_b32_e32 v45, 0xffff0000, v73
	v_pk_mul_f32 v[42:43], v[42:43], v[44:45]
	v_cvt_pk_f16_f32 v40, v40, v41
	v_cvt_pk_f16_f32 v41, v42, v43
	v_lshl_add_u64 v[42:43], s[12:13], 0, v[70:71]
	global_store_dwordx2 v[42:43], v[40:41], off
	s_waitcnt vmcnt(31)
	v_mov_b32_e32 v76, v210
	v_mov_b32_e32 v77, v211
	v_lshlrev_b32_e32 v40, 16, v76
	v_and_b32_e32 v41, 0xffff0000, v76
	v_pk_mul_f32 v[36:37], v[36:37], v[40:41]
	v_lshlrev_b32_e32 v40, 16, v77
	v_and_b32_e32 v41, 0xffff0000, v77
	v_pk_mul_f32 v[38:39], v[38:39], v[40:41]
	v_cvt_pk_f16_f32 v36, v36, v37
	v_cvt_pk_f16_f32 v37, v38, v39
	v_lshl_add_u64 v[38:39], s[12:13], 0, v[74:75]
	global_store_dwordx2 v[38:39], v[36:37], off
	s_waitcnt vmcnt(31)
	v_mov_b32_e32 v80, v212
	v_mov_b32_e32 v81, v213
	v_lshlrev_b32_e32 v36, 16, v80
	v_and_b32_e32 v37, 0xffff0000, v80
	v_pk_mul_f32 v[32:33], v[32:33], v[36:37]
	v_lshlrev_b32_e32 v36, 16, v81
	v_and_b32_e32 v37, 0xffff0000, v81
	v_pk_mul_f32 v[34:35], v[34:35], v[36:37]
	v_cvt_pk_f16_f32 v32, v32, v33
	v_cvt_pk_f16_f32 v33, v34, v35
	v_lshl_add_u64 v[34:35], s[12:13], 0, v[78:79]
	global_store_dwordx2 v[34:35], v[32:33], off
	v_add_u32_e32 v32, 0x3800, v130
	v_add_u32_e32 v36, 0x3a00, v130
	v_add_u32_e32 v40, 0x3c00, v130
	v_add_u32_e32 v44, 0x3e00, v130
	v_ashrrev_i32_e32 v33, 31, v32
	v_ashrrev_i32_e32 v37, 31, v36
	v_ashrrev_i32_e32 v41, 31, v40
	v_ashrrev_i32_e32 v45, 31, v44
	v_lshlrev_b64 v[32:33], 3, v[32:33]
	v_lshlrev_b64 v[36:37], 3, v[36:37]
	v_lshlrev_b64 v[40:41], 3, v[40:41]
	v_lshlrev_b64 v[44:45], 3, v[44:45]
	v_lshl_add_u64 v[34:35], s[10:11], 0, v[32:33]
	v_lshl_add_u64 v[38:39], s[10:11], 0, v[36:37]
	v_lshl_add_u64 v[42:43], s[10:11], 0, v[40:41]
	v_lshl_add_u64 v[46:47], s[10:11], 0, v[44:45]
	s_nop 0
	s_nop 0
	s_nop 0
	s_waitcnt vmcnt(31)
	v_mov_b32_e32 v50, v222
	v_mov_b32_e32 v51, v223
	v_lshlrev_b32_e32 v66, 16, v50
	v_and_b32_e32 v67, 0xffff0000, v50
	v_lshlrev_b32_e32 v50, 16, v51
	v_and_b32_e32 v51, 0xffff0000, v51
	v_pk_mul_f32 v[28:29], v[28:29], v[66:67]
	v_pk_mul_f32 v[30:31], v[30:31], v[50:51]
	v_cvt_pk_f16_f32 v28, v28, v29
	v_cvt_pk_f16_f32 v29, v30, v31
	v_lshl_add_u64 v[30:31], s[12:13], 0, v[48:49]
	global_store_dwordx2 v[30:31], v[28:29], off
	s_waitcnt vmcnt(31)
	v_mov_b32_e32 v54, v224
	v_mov_b32_e32 v55, v225
	v_lshlrev_b32_e32 v28, 16, v54
	v_and_b32_e32 v29, 0xffff0000, v54
	v_pk_mul_f32 v[24:25], v[24:25], v[28:29]
	v_lshlrev_b32_e32 v28, 16, v55
	v_and_b32_e32 v29, 0xffff0000, v55
	v_pk_mul_f32 v[26:27], v[26:27], v[28:29]
	v_cvt_pk_f16_f32 v24, v24, v25
	v_cvt_pk_f16_f32 v25, v26, v27
	v_lshl_add_u64 v[26:27], s[12:13], 0, v[52:53]
	global_store_dwordx2 v[26:27], v[24:25], off
	s_waitcnt vmcnt(31)
	v_mov_b32_e32 v58, v226
	v_mov_b32_e32 v59, v227
	v_lshlrev_b32_e32 v24, 16, v58
	v_and_b32_e32 v25, 0xffff0000, v58
	v_pk_mul_f32 v[20:21], v[20:21], v[24:25]
	v_lshlrev_b32_e32 v24, 16, v59
	v_and_b32_e32 v25, 0xffff0000, v59
	v_pk_mul_f32 v[22:23], v[22:23], v[24:25]
	v_cvt_pk_f16_f32 v20, v20, v21
	v_cvt_pk_f16_f32 v21, v22, v23
	v_lshl_add_u64 v[22:23], s[12:13], 0, v[56:57]
	global_store_dwordx2 v[22:23], v[20:21], off
	s_waitcnt vmcnt(31)
	v_mov_b32_e32 v62, v228
	v_mov_b32_e32 v63, v229
	v_lshlrev_b32_e32 v20, 16, v62
	v_and_b32_e32 v21, 0xffff0000, v62
	v_pk_mul_f32 v[16:17], v[16:17], v[20:21]
	v_lshlrev_b32_e32 v20, 16, v63
	v_and_b32_e32 v21, 0xffff0000, v63
	v_pk_mul_f32 v[18:19], v[18:19], v[20:21]
	v_cvt_pk_f16_f32 v16, v16, v17
	v_cvt_pk_f16_f32 v17, v18, v19
	v_lshl_add_u64 v[18:19], s[12:13], 0, v[60:61]
	global_store_dwordx2 v[18:19], v[16:17], off
	s_waitcnt vmcnt(31)
	v_mov_b32_e32 v34, v230
	v_mov_b32_e32 v35, v231
	v_lshlrev_b32_e32 v16, 16, v34
	v_and_b32_e32 v17, 0xffff0000, v34
	v_pk_mul_f32 v[12:13], v[12:13], v[16:17]
	v_lshlrev_b32_e32 v16, 16, v35
	v_and_b32_e32 v17, 0xffff0000, v35
	v_pk_mul_f32 v[14:15], v[14:15], v[16:17]
	v_cvt_pk_f16_f32 v12, v12, v13
	v_cvt_pk_f16_f32 v13, v14, v15
	v_lshl_add_u64 v[14:15], s[12:13], 0, v[32:33]
	global_store_dwordx2 v[14:15], v[12:13], off
	s_waitcnt vmcnt(31)
	v_mov_b32_e32 v38, v232
	v_mov_b32_e32 v39, v233
	v_lshlrev_b32_e32 v12, 16, v38
	v_and_b32_e32 v13, 0xffff0000, v38
	v_pk_mul_f32 v[8:9], v[8:9], v[12:13]
	v_lshlrev_b32_e32 v12, 16, v39
	v_and_b32_e32 v13, 0xffff0000, v39
	v_pk_mul_f32 v[10:11], v[10:11], v[12:13]
	v_cvt_pk_f16_f32 v8, v8, v9
	v_cvt_pk_f16_f32 v9, v10, v11
	v_lshl_add_u64 v[10:11], s[12:13], 0, v[36:37]
	global_store_dwordx2 v[10:11], v[8:9], off
	s_waitcnt vmcnt(31)
; DI unsigned pk_f16(float lo, float hi) { f32x2_t v = {lo, hi}; return __builtin_bit_cast(unsigned, __builtin_convertvector(v, f16x2_t)); }
; DI float bflo(unsigned u) { return __uint_as_float(u << 16); }
; DI float bfhi(unsigned u) { return __uint_as_float(u & 0xffff0000u); }
; DI int my_tid() { int t = tid_raw(); asm volatile("" : "+v"(t)); return t; }
; #define STAGE_A(b, h, kt) { const u16* ap_ = A + (size_t)((h) * ahalf + (unsigned)(kt) * 64u); glds16(ap_ + ao0, l0 + SA_(b, h)); glds16(ap_ + ao1, l0 + SA_(b, h) + 8192); }
; #define STAGE_B(b, h, kt) { const u16* bp_ = ((h) ? B1 : B0) + (unsigned)(kt) * 64u; glds16(bp_ + bo0, l0 + SB_(b, h)); glds16(bp_ + bo1, l0 + SB_(b, h) + 8192); }
; DI void gemm256(const u16* __restrict__ A, int lda, const u16* __restrict__ B0, const u16* __restrict__ B1, int ldb, int nt, acc_t& acc, char* lds) {
;   const int tid = my_tid();
;   const int lane = tid & 63, wid = tid >> 6, wr = wid >> 2, wc = wid & 3, fr = lane & 15, fq = lane >> 4;
;   int r0, c0, r1, c1;
;   stage_rc(tid * 16, r0, c0); stage_rc(tid * 16 + 8192, r1, c1);
;   const unsigned ao0 = (unsigned)(r0 * lda + c0), ao1 = (unsigned)(r1 * lda + c1);
;   const unsigned ahalf = 128u * (unsigned)lda;
;   const int p0 = (r0 & ~31) + (((r0 & 15) >> 2) * 8) + (((r0 >> 4) & 1) * 4) + (r0 & 3), p1 = (r1 & ~31) + (((r1 & 15) >> 2) * 8) + (((r1 >> 4) & 1) * 4) + (r1 & 3);
;   const unsigned bo0 = (unsigned)(p0 * ldb + c0), bo1 = (unsigned)(p1 * ldb + c1);
;   char* l0 = lds + tid * 16;
;     ...
;   bf16x8 At[4][2], Bq0[2][2], Bq1[2][2];
;   WAIT_V(0)
;   STAGE_B(0, 0, 0) STAGE_A(0, 0, 0) STAGE_B(0, 1, 0) STAGE_A(0, 1, 0)
;   if (wr == 1) BAR
;   WAIT_V(4) BAR
;   STAGE_B(1, 0, 1) STAGE_A(1, 0, 1) STAGE_B(1, 1, 1)
;   WAIT_V(6) BAR
; DI void p5_phase(const Params& p, char* lds) {
;     ...
;       EPI_M {
;         if (m < 7) EPI_N gq[(m + 1) & 1][n] = tg[((m + 1) * 4 + n) * 512 + tid];
;         EPI_N {
;           const u32x2 g = gq[m & 1][n];
;           u32x2 o; o[0] = pk_f16(ACC(m, n)[0] * bflo(g[0]), ACC(m, n)[1] * bfhi(g[0])); o[1] = pk_f16(ACC(m, n)[2] * bflo(g[1]), ACC(m, n)[3] * bfhi(g[1]));
;           tr[(m * 4 + n) * 512 + tid] = o;
;         }
;         __builtin_amdgcn_sched_barrier(0);
;       }
;     }
;     zero_acc(acc);
;     gemm256(xb + (size_t)row0 * D, D, win + (size_t)(4608 + col0) * D, win + (size_t)(4608 + col0 + 128) * D, D, 16, acc, lds);
	v_mov_b32_e32 v42, v234
	v_mov_b32_e32 v43, v235
	v_lshlrev_b32_e32 v8, 16, v42
	v_and_b32_e32 v9, 0xffff0000, v42
	v_pk_mul_f32 v[4:5], v[4:5], v[8:9]
	v_lshlrev_b32_e32 v8, 16, v43
	v_and_b32_e32 v9, 0xffff0000, v43
	v_pk_mul_f32 v[6:7], v[6:7], v[8:9]
	v_cvt_pk_f16_f32 v4, v4, v5
	v_cvt_pk_f16_f32 v5, v6, v7
	v_lshl_add_u64 v[6:7], s[12:13], 0, v[40:41]
	global_store_dwordx2 v[6:7], v[4:5], off
	s_waitcnt vmcnt(31)
	v_mov_b32_e32 v46, v236
	v_mov_b32_e32 v47, v237
	v_lshlrev_b32_e32 v4, 16, v46
	v_and_b32_e32 v5, 0xffff0000, v46
	v_pk_mul_f32 v[0:1], v[0:1], v[4:5]
	v_lshlrev_b32_e32 v4, 16, v47
	v_and_b32_e32 v5, 0xffff0000, v47
	v_pk_mul_f32 v[2:3], v[2:3], v[4:5]
	v_cvt_pk_f16_f32 v0, v0, v1
	v_cvt_pk_f16_f32 v1, v2, v3
	v_lshl_add_u64 v[2:3], s[12:13], 0, v[44:45]
	global_store_dwordx2 v[2:3], v[0:1], off
	s_lshl_b64 s[2:3], s[38:39], 11
	s_add_u32 s2, s90, s2
	s_addc_u32 s3, s91, s3
	s_add_u32 s22, s2, 0x900000
	s_addc_u32 s23, s3, 0
	s_add_u32 s8, s2, 0x940000
	s_getreg_b32 s2, hwreg(HW_REG_HW_ID, 0, 6)
	s_addc_u32 s9, s3, 0
	s_lshl_b32 s2, s2, 2
	s_and_b32 s2, s2, 0xfc
	s_add_i32 s2, s2, 0x20040
	v_mov_b32_e32 v0, s2
	ds_read_b32 v0, v0
	v_mov_b32_e32 v131, v65
	s_waitcnt lgkmcnt(0)
	v_readfirstlane_b32 s2, v0
	s_nop 1
	v_lshl_or_b32 v140, s2, 6, v214
	s_waitcnt vmcnt(0)
	s_nop 0
	v_bfe_i32 v2, v140, 27, 1
	v_lshlrev_b32_e32 v0, 4, v140
	v_lshrrev_b32_e32 v2, 22, v2
	v_add_u32_e32 v2, v0, v2
	v_and_b32_e32 v2, 0xfffffc00, v2
	v_sub_u32_e32 v2, v0, v2
	v_ashrrev_i32_e32 v1, 31, v140
	v_lshrrev_b32_e32 v3, 4, v2
	v_lshrrev_b32_e32 v1, 26, v1
	v_bitop3_b32 v3, v3, v2, 32 bitop3:0x6c
	v_ashrrev_i32_e32 v2, 31, v2
	v_add_u32_e32 v1, v140, v1
	v_lshrrev_b32_e32 v2, 26, v2
	v_ashrrev_i32_e32 v1, 6, v1
	v_add_u32_e32 v2, v3, v2
	v_lshlrev_b32_e32 v4, 3, v1
	v_ashrrev_i32_e32 v2, 6, v2
	v_lshlrev_b32_e32 v1, 5, v1
	v_and_b32_e32 v14, 32, v1
	v_mul_i32_i24_e32 v1, 64, v2
	v_sub_u32_e32 v1, v3, v1
	v_add_u32_e32 v3, 0x2000, v0
	v_ashrrev_i32_e32 v5, 31, v3
	v_lshrrev_b32_e32 v5, 22, v5
	v_add_u32_e32 v5, v3, v5
	v_ashrrev_i32_e32 v13, 10, v5
	v_mul_i32_i24_e32 v5, 0x400, v13
	v_sub_u32_e32 v3, v3, v5
	v_lshrrev_b32_e32 v5, 4, v3
	v_bitop3_b32 v3, v5, v3, 32 bitop3:0x6c
	v_ashrrev_i32_e32 v6, 31, v3
	v_lshrrev_b32_e32 v6, 26, v6
	v_and_b32_e32 v4, -16, v4
	v_ashrrev_i16_sdwa v15, v215, sext(v1) dst_sel:DWORD dst_unused:UNUSED_PAD src0_sel:DWORD src1_sel:BYTE_0
	v_lshlrev_b32_e32 v5, 3, v13
	v_add_u32_e32 v6, v3, v6
	v_add_u32_e32 v4, v2, v4
	v_add_u32_sdwa v1, v14, sext(v15) dst_sel:DWORD dst_unused:UNUSED_PAD src0_sel:DWORD src1_sel:WORD_0
	v_and_b32_e32 v5, -16, v5
	v_ashrrev_i32_e32 v16, 6, v6
	v_and_b32_e32 v6, 0xc0, v6
	v_add_u32_e32 v5, v16, v5
	v_sub_u32_e32 v3, v3, v6
	v_lshl_add_u32 v8, v4, 10, v1
	v_and_b32_e32 v19, 0xffffffe0, v4
	v_lshlrev_b32_e32 v6, 1, v4
	v_lshrrev_b32_e32 v4, 2, v4
	v_and_b32_e32 v22, 4, v4
	v_and_b32_e32 v24, 3, v2
	v_lshlrev_b32_e32 v4, 1, v5
	v_lshlrev_b32_e32 v7, 5, v13
	v_and_b32_e32 v21, 24, v6
	v_or_b32_e32 v2, v19, v24
	v_and_b32_e32 v20, 0xffffffe0, v5
	v_and_b32_e32 v23, 24, v4
	v_lshrrev_b32_e32 v4, 2, v5
	v_and_b32_e32 v26, 3, v16
	v_and_b32_e32 v17, 32, v7
	v_ashrrev_i16_sdwa v18, v215, sext(v3) dst_sel:DWORD dst_unused:UNUSED_PAD src0_sel:DWORD src1_sel:BYTE_0
	v_or3_b32 v2, v2, v21, v22
	v_and_b32_e32 v25, 4, v4
	v_or_b32_e32 v4, v20, v26
	v_add_u32_e32 v150, 0, v0
	v_add_u32_sdwa v3, v17, sext(v18) dst_sel:DWORD dst_unused:UNUSED_PAD src0_sel:DWORD src1_sel:WORD_0
	v_or3_b32 v4, v4, v23, v25
	v_lshl_add_u32 v64, v2, 10, v1
	v_add_u32_e32 v151, 0x10000, v150
	v_lshl_add_u32 v130, v5, 10, v3
	v_lshl_add_u32 v2, v4, 10, v3
	v_lshlrev_b64 v[6:7], 1, v[64:65]
	v_readfirstlane_b32 s2, v151
	v_mov_b32_e32 v3, v65
	v_add_u32_e32 v152, 0x12000, v150
	v_lshl_add_u64 v[0:1], s[22:23], 0, v[6:7]
	s_mov_b32 m0, s2
	v_lshlrev_b64 v[28:29], 1, v[2:3]
	v_readfirstlane_b32 s2, v152
	v_mov_b32_e32 v64, v8
	global_load_lds_dwordx4 v[0:1], off
	v_lshl_add_u64 v[2:3], s[22:23], 0, v[28:29]
	s_mov_b32 m0, s2
	v_lshlrev_b64 v[30:31], 1, v[64:65]
	v_readfirstlane_b32 s2, v150
	v_add_u32_e32 v153, 0x2000, v150
	global_load_lds_dwordx4 v[2:3], off
	v_lshl_add_u64 v[4:5], s[50:51], 0, v[30:31]
	s_mov_b32 m0, s2
	v_lshlrev_b64 v[32:33], 1, v[130:131]
	v_readfirstlane_b32 s2, v153
	v_add_u32_e32 v155, 0x14000, v150
	global_load_lds_dwordx4 v[4:5], off
	v_lshl_add_u64 v[8:9], s[50:51], 0, v[32:33]
	s_mov_b32 m0, s2
	v_readfirstlane_b32 s2, v155
	v_add_u32_e32 v156, 0x16000, v150
	global_load_lds_dwordx4 v[8:9], off
	v_lshl_add_u64 v[10:11], s[8:9], 0, v[6:7]
	s_mov_b32 m0, s2
	v_readfirstlane_b32 s2, v156
	v_add_u32_e32 v157, 0x4000, v150
	global_load_lds_dwordx4 v[10:11], off
	v_lshl_add_u64 v[6:7], s[8:9], 0, v[28:29]
	s_mov_b32 m0, s2
	v_readfirstlane_b32 s2, v157
	v_add_u32_e32 v158, 0x6000, v150
	global_load_lds_dwordx4 v[6:7], off
	v_lshl_add_u64 v[28:29], s[52:53], 0, v[30:31]
	s_mov_b32 m0, s2
	v_readfirstlane_b32 s2, v158
	global_load_lds_dwordx4 v[28:29], off
	v_lshl_add_u64 v[28:29], s[52:53], 0, v[32:33]
	s_mov_b32 m0, s2
	v_ashrrev_i32_e32 v12, 8, v140
	global_load_lds_dwordx4 v[28:29], off
	v_cmp_eq_u32_e32 vcc, 1, v12
	s_and_saveexec_b64 s[8:9], vcc
	s_cbranch_execz .LBB0_984
	s_barrier

; DI unsigned pk_f16(float lo, float hi) { f32x2_t v = {lo, hi}; return __builtin_bit_cast(unsigned, __builtin_convertvector(v, f16x2_t)); }
; DI float bflo(unsigned u) { return __uint_as_float(u << 16); }
; DI float bfhi(unsigned u) { return __uint_as_float(u & 0xffff0000u); }
; #define EPI_M _Pragma("unroll") for (int m = 0; m < 8; ++m)
; #define EPI_N2 _Pragma("unroll") for (int n2 = 0; n2 < 2; ++n2)
; DI void p6_phase(const Params& p, const float* xin, u16* dst, char* lds) {
;     ...
;     {
;       const u16* xinb = (const u16*)(ws + OFF_XB);
;       u32x4 xq[2][2];
;       EPI_N2 xq[0][n2] = *(const u32x4*)(xinb + (size_t)EPI_ROW(row0, 0) * D + EPI_COL(col0, 2 * n2));
;       EPI_M {
;         if (m < 7) EPI_N2 xq[(m + 1) & 1][n2] = *(const u32x4*)(xinb + (size_t)EPI_ROW(row0, m + 1) * D + EPI_COL(col0, 2 * n2));
;         EPI_N2 {
;           const u32x4 r = xq[m & 1][n2];
;           const f32x4 xa = {bflo(r[0]), bfhi(r[0]), bflo(r[1]), bfhi(r[1])}, xc = {bflo(r[2]), bfhi(r[2]), bflo(r[3]), bfhi(r[3])};
;           const f32x4 ya = xa * DN_ALPHA + ACC(m, 2 * n2), yc = xc * DN_ALPHA + ACC(m, 2 * n2 + 1);
;           u32x4 yo; yo[0] = pk_f16(ya[0], ya[1]); yo[1] = pk_f16(ya[2], ya[3]); yo[2] = pk_f16(yc[0], yc[1]); yo[3] = pk_f16(yc[2], yc[3]);
;           *(u32x4*)(dst + (size_t)EPI_ROW(row0, m) * D + EPI_COL(col0, 2 * n2)) = yo;
;         }
;         __builtin_amdgcn_sched_barrier(0);
;       }
;     }
.LBB0_1049:
	s_or_b64 exec, exec, s[28:29]
	s_waitcnt vmcnt(0)
	s_barrier
	s_getreg_b32 s3, hwreg(HW_REG_HW_ID, 0, 6)
	s_lshl_b32 s3, s3, 2
	s_and_b32 s3, s3, 0xfc
	s_add_i32 s3, s3, 0x20040
	v_mov_b32_e32 v64, s3
	ds_read_b32 v64, v64
	v_readlane_b32 s28, v254, 22
	v_readlane_b32 s29, v254, 23
	s_waitcnt lgkmcnt(0)
	v_readfirstlane_b32 s3, v64
	s_nop 1
	v_lshl_or_b32 v64, s3, 6, v214
	s_nop 0
	v_ashrrev_i32_e32 v122, 2, v64
	v_and_b32_e32 v137, 0xffffffc0, v122
	v_and_b32_e32 v136, 15, v64
	v_add_u32_e32 v122, s8, v137
	v_lshrrev_b32_e32 v64, 1, v64
	v_or_b32_e32 v122, v122, v136
	v_and_b32_e32 v64, 0x78, v64
	v_ashrrev_i32_e32 v123, 31, v122
	v_or_b32_e32 v124, s22, v64
	v_lshlrev_b64 v[122:123], 11, v[122:123]
	v_ashrrev_i32_e32 v125, 31, v124
	v_lshl_add_u64 v[122:123], s[28:29], 0, v[122:123]
	v_lshlrev_b64 v[134:135], 1, v[124:125]
	v_or_b32_e32 v64, s8, v136
	v_lshl_add_u64 v[122:123], v[122:123], 0, v[134:135]
	v_add_u32_e32 v136, v64, v137
	s_mov_b32 s101, 0
	global_load_dwordx4 v[158:161], v[122:123], off
	global_load_dwordx4 v[162:165], v[122:123], off offset:256
	s_mov_b32 s100, 0x8000
	v_lshl_add_u64 v[224:225], v[122:123], 0, s[100:101]
	global_load_dwordx4 v[166:169], v[224:225], off
	global_load_dwordx4 v[170:173], v[224:225], off offset:256
	s_mov_b32 s100, 0x10000
	v_lshl_add_u64 v[224:225], v[122:123], 0, s[100:101]
	global_load_dwordx4 v[174:177], v[224:225], off
	global_load_dwordx4 v[178:181], v[224:225], off offset:256
	s_mov_b32 s100, 0x18000
	v_lshl_add_u64 v[224:225], v[122:123], 0, s[100:101]
	global_load_dwordx4 v[182:185], v[224:225], off
	global_load_dwordx4 v[186:189], v[224:225], off offset:256
	s_mov_b32 s100, 0x40000
	v_lshl_add_u64 v[224:225], v[122:123], 0, s[100:101]
	global_load_dwordx4 v[190:193], v[224:225], off
	global_load_dwordx4 v[194:197], v[224:225], off offset:256
	s_mov_b32 s100, 0x48000
	v_lshl_add_u64 v[224:225], v[122:123], 0, s[100:101]
	global_load_dwordx4 v[198:201], v[224:225], off
	global_load_dwordx4 v[202:205], v[224:225], off offset:256
	s_mov_b32 s100, 0x50000
	v_lshl_add_u64 v[224:225], v[122:123], 0, s[100:101]
	global_load_dwordx4 v[206:209], v[224:225], off
	global_load_dwordx4 v[210:213], v[224:225], off offset:256
	s_mov_b32 s100, 0x58000
	v_lshl_add_u64 v[224:225], v[122:123], 0, s[100:101]
	global_load_dwordx4 v[216:219], v[224:225], off
	global_load_dwordx4 v[226:229], v[224:225], off offset:256
	v_or_b32_e32 v122, 16, v136
	v_ashrrev_i32_e32 v123, 31, v122
	v_lshlrev_b64 v[150:151], 11, v[122:123]
	v_lshl_add_u64 v[122:123], s[28:29], 0, v[150:151]
	v_lshl_add_u64 v[122:123], v[122:123], 0, v[134:135]
	s_nop 0
	v_ashrrev_i32_e32 v137, 31, v136
	v_readlane_b32 s8, v254, 14
	v_lshlrev_b64 v[152:153], 11, v[136:137]
	v_readlane_b32 s9, v254, 15
	s_waitcnt vmcnt(15)
	v_mov_b32_e32 v138, v158
	v_mov_b32_e32 v139, v159
	v_mov_b32_e32 v140, v160
	v_mov_b32_e32 v141, v161
	v_lshlrev_b32_e32 v154, 16, v138
	v_and_b32_e32 v155, 0xffff0000, v138
	v_lshlrev_b32_e32 v138, 16, v139
	v_and_b32_e32 v139, 0xffff0000, v139
	v_lshlrev_b32_e32 v156, 16, v140
	v_and_b32_e32 v157, 0xffff0000, v140
	v_lshlrev_b32_e32 v140, 16, v141
	v_and_b32_e32 v141, 0xffff0000, v141
	v_lshl_add_u64 v[152:153], s[8:9], 0, v[152:153]
	v_pk_fma_f32 v[128:129], v[138:139], s[78:79], v[128:129] op_sel_hi:[1,0,1]
	v_pk_fma_f32 v[126:127], v[154:155], s[78:79], v[126:127] op_sel_hi:[1,0,1]
	v_pk_fma_f32 v[132:133], v[140:141], s[78:79], v[132:133] op_sel_hi:[1,0,1]
	v_pk_fma_f32 v[130:131], v[156:157], s[78:79], v[130:131] op_sel_hi:[1,0,1]
	v_cvt_pk_f16_f32 v126, v126, v127
	v_cvt_pk_f16_f32 v127, v128, v129
	v_cvt_pk_f16_f32 v128, v130, v131
	v_cvt_pk_f16_f32 v129, v132, v133
	v_lshl_add_u64 v[130:131], v[152:153], 0, v[134:135]
	global_store_dwordx4 v[130:131], v[126:129], off
	s_waitcnt vmcnt(15)
	v_mov_b32_e32 v142, v162
	v_mov_b32_e32 v143, v163
	v_mov_b32_e32 v144, v164
	v_mov_b32_e32 v145, v165
	v_lshlrev_b32_e32 v132, 16, v144
	v_and_b32_e32 v133, 0xffff0000, v144
	v_lshlrev_b32_e32 v126, 16, v142
	v_and_b32_e32 v127, 0xffff0000, v142
	v_lshlrev_b32_e32 v128, 16, v143
	v_and_b32_e32 v129, 0xffff0000, v143
	v_lshlrev_b32_e32 v138, 16, v145
	v_and_b32_e32 v139, 0xffff0000, v145
	v_pk_fma_f32 v[120:121], v[128:129], s[78:79], v[120:121] op_sel_hi:[1,0,1]
	v_pk_fma_f32 v[118:119], v[126:127], s[78:79], v[118:119] op_sel_hi:[1,0,1]
	v_pk_fma_f32 v[126:127], v[138:139], s[78:79], v[116:117] op_sel_hi:[1,0,1]
	v_pk_fma_f32 v[116:117], v[132:133], s[78:79], v[114:115] op_sel_hi:[1,0,1]
	v_cvt_pk_f16_f32 v114, v118, v119
	v_cvt_pk_f16_f32 v115, v120, v121
	v_cvt_pk_f16_f32 v116, v116, v117
	v_cvt_pk_f16_f32 v117, v126, v127
	global_store_dwordx4 v[130:131], v[114:117], off offset:256
	s_nop 1
	v_or_b32_e32 v114, 32, v136
	v_ashrrev_i32_e32 v115, 31, v114
	v_lshlrev_b64 v[126:127], 11, v[114:115]
	v_lshl_add_u64 v[114:115], s[28:29], 0, v[126:127]
	v_lshl_add_u64 v[118:119], v[114:115], 0, v[134:135]
	s_nop 0
	s_waitcnt vmcnt(15)
	v_mov_b32_e32 v146, v166
	v_mov_b32_e32 v147, v167
	v_mov_b32_e32 v148, v168
	v_mov_b32_e32 v149, v169
	v_lshlrev_b32_e32 v130, 16, v146
	v_and_b32_e32 v131, 0xffff0000, v146
	v_lshlrev_b32_e32 v132, 16, v147
	v_and_b32_e32 v133, 0xffff0000, v147
	v_lshlrev_b32_e32 v138, 16, v148
	v_and_b32_e32 v139, 0xffff0000, v148
	v_lshlrev_b32_e32 v140, 16, v149
	v_and_b32_e32 v141, 0xffff0000, v149
	v_lshl_add_u64 v[128:129], s[8:9], 0, v[150:151]
	v_pk_fma_f32 v[112:113], v[132:133], s[78:79], v[112:113] op_sel_hi:[1,0,1]
	v_pk_fma_f32 v[110:111], v[130:131], s[78:79], v[110:111] op_sel_hi:[1,0,1]
	v_pk_fma_f32 v[130:131], v[140:141], s[78:79], v[108:109] op_sel_hi:[1,0,1]
	v_pk_fma_f32 v[108:109], v[138:139], s[78:79], v[106:107] op_sel_hi:[1,0,1]
	v_cvt_pk_f16_f32 v106, v110, v111
	v_cvt_pk_f16_f32 v107, v112, v113
	v_cvt_pk_f16_f32 v108, v108, v109
	v_cvt_pk_f16_f32 v109, v130, v131
	v_lshl_add_u64 v[110:111], v[128:129], 0, v[134:135]
	global_store_dwordx4 v[110:111], v[106:109], off
	s_waitcnt vmcnt(15)
; DI unsigned pk_f16(float lo, float hi) { f32x2_t v = {lo, hi}; return __builtin_bit_cast(unsigned, __builtin_convertvector(v, f16x2_t)); }
; DI float bflo(unsigned u) { return __uint_as_float(u << 16); }
; DI float bfhi(unsigned u) { return __uint_as_float(u & 0xffff0000u); }
; #define EPI_M _Pragma("unroll") for (int m = 0; m < 8; ++m)
; #define EPI_N2 _Pragma("unroll") for (int n2 = 0; n2 < 2; ++n2)
; DI void p6_phase(const Params& p, const float* xin, u16* dst, char* lds) {
;     ...
;       EPI_N2 xq[0][n2] = *(const u32x4*)(xinb + (size_t)EPI_ROW(row0, 0) * D + EPI_COL(col0, 2 * n2));
;       EPI_M {
;         if (m < 7) EPI_N2 xq[(m + 1) & 1][n2] = *(const u32x4*)(xinb + (size_t)EPI_ROW(row0, m + 1) * D + EPI_COL(col0, 2 * n2));
;         EPI_N2 {
;           const u32x4 r = xq[m & 1][n2];
;           const f32x4 xa = {bflo(r[0]), bfhi(r[0]), bflo(r[1]), bfhi(r[1])}, xc = {bflo(r[2]), bfhi(r[2]), bflo(r[3]), bfhi(r[3])};
;           const f32x4 ya = xa * DN_ALPHA + ACC(m, 2 * n2), yc = xc * DN_ALPHA + ACC(m, 2 * n2 + 1);
;           u32x4 yo; yo[0] = pk_f16(ya[0], ya[1]); yo[1] = pk_f16(ya[2], ya[3]); yo[2] = pk_f16(yc[0], yc[1]); yo[3] = pk_f16(yc[2], yc[3]);
;           *(u32x4*)(dst + (size_t)EPI_ROW(row0, m) * D + EPI_COL(col0, 2 * n2)) = yo;
;         }
;         __builtin_amdgcn_sched_barrier(0);
;       }
	v_mov_b32_e32 v122, v170
	v_mov_b32_e32 v123, v171
	v_mov_b32_e32 v124, v172
	v_mov_b32_e32 v125, v173
	v_lshlrev_b32_e32 v112, 16, v124
	v_and_b32_e32 v113, 0xffff0000, v124
	v_lshlrev_b32_e32 v106, 16, v122
	v_and_b32_e32 v107, 0xffff0000, v122
	v_lshlrev_b32_e32 v108, 16, v123
	v_and_b32_e32 v109, 0xffff0000, v123
	v_lshlrev_b32_e32 v122, 16, v125
	v_and_b32_e32 v123, 0xffff0000, v125
	v_pk_fma_f32 v[104:105], v[108:109], s[78:79], v[104:105] op_sel_hi:[1,0,1]
	v_pk_fma_f32 v[102:103], v[106:107], s[78:79], v[102:103] op_sel_hi:[1,0,1]
	v_pk_fma_f32 v[106:107], v[122:123], s[78:79], v[100:101] op_sel_hi:[1,0,1]
	v_pk_fma_f32 v[100:101], v[112:113], s[78:79], v[98:99] op_sel_hi:[1,0,1]
	v_cvt_pk_f16_f32 v98, v102, v103
	v_cvt_pk_f16_f32 v99, v104, v105
	v_cvt_pk_f16_f32 v100, v100, v101
	v_cvt_pk_f16_f32 v101, v106, v107
	global_store_dwordx4 v[110:111], v[98:101], off offset:256
	s_nop 1
	v_or_b32_e32 v98, 48, v136
	v_ashrrev_i32_e32 v99, 31, v98
	v_lshlrev_b64 v[106:107], 11, v[98:99]
	v_lshl_add_u64 v[98:99], s[28:29], 0, v[106:107]
	v_lshl_add_u64 v[102:103], v[98:99], 0, v[134:135]
	s_nop 0
	s_waitcnt vmcnt(15)
	v_mov_b32_e32 v114, v174
	v_mov_b32_e32 v115, v175
	v_mov_b32_e32 v116, v176
	v_mov_b32_e32 v117, v177
	v_lshlrev_b32_e32 v110, 16, v114
	v_and_b32_e32 v111, 0xffff0000, v114
	v_lshlrev_b32_e32 v112, 16, v115
	v_and_b32_e32 v113, 0xffff0000, v115
	v_lshlrev_b32_e32 v114, 16, v116
	v_and_b32_e32 v115, 0xffff0000, v116
	v_lshlrev_b32_e32 v116, 16, v117
	v_and_b32_e32 v117, 0xffff0000, v117
	v_lshl_add_u64 v[108:109], s[8:9], 0, v[126:127]
	v_pk_fma_f32 v[96:97], v[112:113], s[78:79], v[96:97] op_sel_hi:[1,0,1]
	v_pk_fma_f32 v[94:95], v[110:111], s[78:79], v[94:95] op_sel_hi:[1,0,1]
	v_pk_fma_f32 v[110:111], v[116:117], s[78:79], v[92:93] op_sel_hi:[1,0,1]
	v_pk_fma_f32 v[92:93], v[114:115], s[78:79], v[90:91] op_sel_hi:[1,0,1]
	v_cvt_pk_f16_f32 v90, v94, v95
	v_cvt_pk_f16_f32 v91, v96, v97
	v_cvt_pk_f16_f32 v92, v92, v93
	v_cvt_pk_f16_f32 v93, v110, v111
	v_lshl_add_u64 v[94:95], v[108:109], 0, v[134:135]
	global_store_dwordx4 v[94:95], v[90:93], off
	s_waitcnt vmcnt(15)
	v_mov_b32_e32 v118, v178
	v_mov_b32_e32 v119, v179
	v_mov_b32_e32 v120, v180
	v_mov_b32_e32 v121, v181
	v_lshlrev_b32_e32 v96, 16, v120
	v_and_b32_e32 v97, 0xffff0000, v120
	v_lshlrev_b32_e32 v90, 16, v118
	v_and_b32_e32 v91, 0xffff0000, v118
	v_lshlrev_b32_e32 v92, 16, v119
	v_and_b32_e32 v93, 0xffff0000, v119
	v_lshlrev_b32_e32 v108, 16, v121
	v_and_b32_e32 v109, 0xffff0000, v121
	v_pk_fma_f32 v[88:89], v[92:93], s[78:79], v[88:89] op_sel_hi:[1,0,1]
	v_pk_fma_f32 v[86:87], v[90:91], s[78:79], v[86:87] op_sel_hi:[1,0,1]
	v_pk_fma_f32 v[90:91], v[108:109], s[78:79], v[84:85] op_sel_hi:[1,0,1]
	v_pk_fma_f32 v[84:85], v[96:97], s[78:79], v[82:83] op_sel_hi:[1,0,1]
	v_cvt_pk_f16_f32 v82, v86, v87
	v_cvt_pk_f16_f32 v83, v88, v89
	v_cvt_pk_f16_f32 v84, v84, v85
	v_cvt_pk_f16_f32 v85, v90, v91
	global_store_dwordx4 v[94:95], v[82:85], off offset:256
	s_nop 1
	v_add_u32_e32 v82, 0x80, v136
	v_ashrrev_i32_e32 v83, 31, v82
	v_lshlrev_b64 v[90:91], 11, v[82:83]
	v_lshl_add_u64 v[82:83], s[28:29], 0, v[90:91]
	v_lshl_add_u64 v[86:87], v[82:83], 0, v[134:135]
	s_nop 0
	s_waitcnt vmcnt(15)
	v_mov_b32_e32 v98, v182
	v_mov_b32_e32 v99, v183
	v_mov_b32_e32 v100, v184
	v_mov_b32_e32 v101, v185
	v_lshlrev_b32_e32 v94, 16, v98
	v_and_b32_e32 v95, 0xffff0000, v98
	v_lshlrev_b32_e32 v96, 16, v99
	v_and_b32_e32 v97, 0xffff0000, v99
	v_lshlrev_b32_e32 v98, 16, v100
	v_and_b32_e32 v99, 0xffff0000, v100
	v_lshlrev_b32_e32 v100, 16, v101
	v_and_b32_e32 v101, 0xffff0000, v101
	v_lshl_add_u64 v[92:93], s[8:9], 0, v[106:107]
	v_pk_fma_f32 v[80:81], v[96:97], s[78:79], v[80:81] op_sel_hi:[1,0,1]
	v_pk_fma_f32 v[78:79], v[94:95], s[78:79], v[78:79] op_sel_hi:[1,0,1]
	v_pk_fma_f32 v[94:95], v[100:101], s[78:79], v[76:77] op_sel_hi:[1,0,1]
	v_pk_fma_f32 v[76:77], v[98:99], s[78:79], v[74:75] op_sel_hi:[1,0,1]
	v_cvt_pk_f16_f32 v74, v78, v79
	v_cvt_pk_f16_f32 v75, v80, v81
	v_cvt_pk_f16_f32 v76, v76, v77
	v_cvt_pk_f16_f32 v77, v94, v95
	v_lshl_add_u64 v[78:79], v[92:93], 0, v[134:135]
	global_store_dwordx4 v[78:79], v[74:77], off
	s_waitcnt vmcnt(15)
	v_mov_b32_e32 v102, v186
	v_mov_b32_e32 v103, v187
	v_mov_b32_e32 v104, v188
	v_mov_b32_e32 v105, v189
	v_lshlrev_b32_e32 v80, 16, v104
	v_and_b32_e32 v81, 0xffff0000, v104
	v_lshlrev_b32_e32 v74, 16, v102
	v_and_b32_e32 v75, 0xffff0000, v102
	v_lshlrev_b32_e32 v76, 16, v103
	v_and_b32_e32 v77, 0xffff0000, v103
	v_lshlrev_b32_e32 v92, 16, v105
	v_and_b32_e32 v93, 0xffff0000, v105
	v_pk_fma_f32 v[72:73], v[76:77], s[78:79], v[72:73] op_sel_hi:[1,0,1]
	v_pk_fma_f32 v[70:71], v[74:75], s[78:79], v[70:71] op_sel_hi:[1,0,1]
	v_pk_fma_f32 v[74:75], v[92:93], s[78:79], v[68:69] op_sel_hi:[1,0,1]
	v_pk_fma_f32 v[68:69], v[80:81], s[78:79], v[66:67] op_sel_hi:[1,0,1]
	v_cvt_pk_f16_f32 v66, v70, v71
	v_cvt_pk_f16_f32 v67, v72, v73
	v_cvt_pk_f16_f32 v68, v68, v69
	v_cvt_pk_f16_f32 v69, v74, v75
	global_store_dwordx4 v[78:79], v[66:69], off offset:256
	s_nop 1
	v_add_u32_e32 v66, 0x90, v136
	v_ashrrev_i32_e32 v67, 31, v66
	v_lshlrev_b64 v[74:75], 11, v[66:67]
	v_lshl_add_u64 v[66:67], s[28:29], 0, v[74:75]
	v_lshl_add_u64 v[70:71], v[66:67], 0, v[134:135]
	s_nop 0
	s_waitcnt vmcnt(15)
; DI unsigned pk_f16(float lo, float hi) { f32x2_t v = {lo, hi}; return __builtin_bit_cast(unsigned, __builtin_convertvector(v, f16x2_t)); }
; DI float bflo(unsigned u) { return __uint_as_float(u << 16); }
; DI float bfhi(unsigned u) { return __uint_as_float(u & 0xffff0000u); }
; #define EPI_M _Pragma("unroll") for (int m = 0; m < 8; ++m)
; #define EPI_N2 _Pragma("unroll") for (int n2 = 0; n2 < 2; ++n2)
; DI void p6_phase(const Params& p, const float* xin, u16* dst, char* lds) {
;     ...
;       EPI_N2 xq[0][n2] = *(const u32x4*)(xinb + (size_t)EPI_ROW(row0, 0) * D + EPI_COL(col0, 2 * n2));
;       EPI_M {
;         if (m < 7) EPI_N2 xq[(m + 1) & 1][n2] = *(const u32x4*)(xinb + (size_t)EPI_ROW(row0, m + 1) * D + EPI_COL(col0, 2 * n2));
;         EPI_N2 {
;           const u32x4 r = xq[m & 1][n2];
;           const f32x4 xa = {bflo(r[0]), bfhi(r[0]), bflo(r[1]), bfhi(r[1])}, xc = {bflo(r[2]), bfhi(r[2]), bflo(r[3]), bfhi(r[3])};
;           const f32x4 ya = xa * DN_ALPHA + ACC(m, 2 * n2), yc = xc * DN_ALPHA + ACC(m, 2 * n2 + 1);
;           u32x4 yo; yo[0] = pk_f16(ya[0], ya[1]); yo[1] = pk_f16(ya[2], ya[3]); yo[2] = pk_f16(yc[0], yc[1]); yo[3] = pk_f16(yc[2], yc[3]);
;           *(u32x4*)(dst + (size_t)EPI_ROW(row0, m) * D + EPI_COL(col0, 2 * n2)) = yo;
;         }
;         __builtin_amdgcn_sched_barrier(0);
;       }
	v_mov_b32_e32 v82, v190
	v_mov_b32_e32 v83, v191
	v_mov_b32_e32 v84, v192
	v_mov_b32_e32 v85, v193
	v_lshlrev_b32_e32 v78, 16, v82
	v_and_b32_e32 v79, 0xffff0000, v82
	v_lshlrev_b32_e32 v80, 16, v83
	v_and_b32_e32 v81, 0xffff0000, v83
	v_lshlrev_b32_e32 v82, 16, v84
	v_and_b32_e32 v83, 0xffff0000, v84
	v_lshlrev_b32_e32 v84, 16, v85
	v_and_b32_e32 v85, 0xffff0000, v85
	v_lshl_add_u64 v[76:77], s[8:9], 0, v[90:91]
	v_pk_fma_f32 v[62:63], v[80:81], s[78:79], v[62:63] op_sel_hi:[1,0,1]
	v_pk_fma_f32 v[60:61], v[78:79], s[78:79], v[60:61] op_sel_hi:[1,0,1]
	v_pk_fma_f32 v[78:79], v[84:85], s[78:79], v[58:59] op_sel_hi:[1,0,1]
	v_pk_fma_f32 v[58:59], v[82:83], s[78:79], v[56:57] op_sel_hi:[1,0,1]
	v_cvt_pk_f16_f32 v56, v60, v61
	v_cvt_pk_f16_f32 v57, v62, v63
	v_cvt_pk_f16_f32 v58, v58, v59
	v_cvt_pk_f16_f32 v59, v78, v79
	v_lshl_add_u64 v[60:61], v[76:77], 0, v[134:135]
	global_store_dwordx4 v[60:61], v[56:59], off
	s_waitcnt vmcnt(15)
	v_mov_b32_e32 v86, v194
	v_mov_b32_e32 v87, v195
	v_mov_b32_e32 v88, v196
	v_mov_b32_e32 v89, v197
	v_lshlrev_b32_e32 v62, 16, v88
	v_and_b32_e32 v63, 0xffff0000, v88
	v_lshlrev_b32_e32 v56, 16, v86
	v_and_b32_e32 v57, 0xffff0000, v86
	v_lshlrev_b32_e32 v58, 16, v87
	v_and_b32_e32 v59, 0xffff0000, v87
	v_lshlrev_b32_e32 v76, 16, v89
	v_and_b32_e32 v77, 0xffff0000, v89
	v_pk_fma_f32 v[54:55], v[58:59], s[78:79], v[54:55] op_sel_hi:[1,0,1]
	v_pk_fma_f32 v[52:53], v[56:57], s[78:79], v[52:53] op_sel_hi:[1,0,1]
	v_pk_fma_f32 v[56:57], v[76:77], s[78:79], v[50:51] op_sel_hi:[1,0,1]
	v_pk_fma_f32 v[50:51], v[62:63], s[78:79], v[48:49] op_sel_hi:[1,0,1]
	v_cvt_pk_f16_f32 v48, v52, v53
	v_cvt_pk_f16_f32 v49, v54, v55
	v_cvt_pk_f16_f32 v50, v50, v51
	v_cvt_pk_f16_f32 v51, v56, v57
	global_store_dwordx4 v[60:61], v[48:51], off offset:256
	s_nop 1
	v_add_u32_e32 v48, 0xa0, v136
	v_ashrrev_i32_e32 v49, 31, v48
	v_lshlrev_b64 v[56:57], 11, v[48:49]
	v_lshl_add_u64 v[48:49], s[28:29], 0, v[56:57]
	v_lshl_add_u64 v[52:53], v[48:49], 0, v[134:135]
	s_nop 0
	s_waitcnt vmcnt(15)
	v_mov_b32_e32 v66, v198
	v_mov_b32_e32 v67, v199
	v_mov_b32_e32 v68, v200
	v_mov_b32_e32 v69, v201
	v_lshlrev_b32_e32 v60, 16, v66
	v_and_b32_e32 v61, 0xffff0000, v66
	v_lshlrev_b32_e32 v62, 16, v67
	v_and_b32_e32 v63, 0xffff0000, v67
	v_lshlrev_b32_e32 v66, 16, v68
	v_and_b32_e32 v67, 0xffff0000, v68
	v_lshlrev_b32_e32 v68, 16, v69
	v_and_b32_e32 v69, 0xffff0000, v69
	v_lshl_add_u64 v[58:59], s[8:9], 0, v[74:75]
	v_pk_fma_f32 v[46:47], v[62:63], s[78:79], v[46:47] op_sel_hi:[1,0,1]
	v_pk_fma_f32 v[44:45], v[60:61], s[78:79], v[44:45] op_sel_hi:[1,0,1]
	v_pk_fma_f32 v[60:61], v[68:69], s[78:79], v[42:43] op_sel_hi:[1,0,1]
	v_pk_fma_f32 v[42:43], v[66:67], s[78:79], v[40:41] op_sel_hi:[1,0,1]
	v_cvt_pk_f16_f32 v40, v44, v45
	v_cvt_pk_f16_f32 v41, v46, v47
	v_cvt_pk_f16_f32 v42, v42, v43
	v_cvt_pk_f16_f32 v43, v60, v61
	v_lshl_add_u64 v[44:45], v[58:59], 0, v[134:135]
	global_store_dwordx4 v[44:45], v[40:43], off
	s_waitcnt vmcnt(15)
	v_mov_b32_e32 v70, v202
	v_mov_b32_e32 v71, v203
	v_mov_b32_e32 v72, v204
	v_mov_b32_e32 v73, v205
	v_lshlrev_b32_e32 v46, 16, v72
	v_and_b32_e32 v47, 0xffff0000, v72
	v_lshlrev_b32_e32 v40, 16, v70
	v_and_b32_e32 v41, 0xffff0000, v70
	v_lshlrev_b32_e32 v42, 16, v71
	v_and_b32_e32 v43, 0xffff0000, v71
	v_lshlrev_b32_e32 v58, 16, v73
	v_and_b32_e32 v59, 0xffff0000, v73
	v_pk_fma_f32 v[38:39], v[42:43], s[78:79], v[38:39] op_sel_hi:[1,0,1]
	v_pk_fma_f32 v[36:37], v[40:41], s[78:79], v[36:37] op_sel_hi:[1,0,1]
	v_pk_fma_f32 v[40:41], v[58:59], s[78:79], v[34:35] op_sel_hi:[1,0,1]
	v_pk_fma_f32 v[34:35], v[46:47], s[78:79], v[32:33] op_sel_hi:[1,0,1]
	v_cvt_pk_f16_f32 v32, v36, v37
	v_cvt_pk_f16_f32 v33, v38, v39
	v_cvt_pk_f16_f32 v34, v34, v35
	v_cvt_pk_f16_f32 v35, v40, v41
	global_store_dwordx4 v[44:45], v[32:35], off offset:256
	s_nop 1
	v_add_u32_e32 v32, 0xb0, v136
	v_ashrrev_i32_e32 v33, 31, v32
	v_lshlrev_b64 v[40:41], 11, v[32:33]
	v_lshl_add_u64 v[32:33], s[28:29], 0, v[40:41]
	v_lshl_add_u64 v[36:37], v[32:33], 0, v[134:135]
	s_nop 0
	s_waitcnt vmcnt(15)
; DI unsigned pk_f16(float lo, float hi) { f32x2_t v = {lo, hi}; return __builtin_bit_cast(unsigned, __builtin_convertvector(v, f16x2_t)); }
; DI float bflo(unsigned u) { return __uint_as_float(u << 16); }
; DI float bfhi(unsigned u) { return __uint_as_float(u & 0xffff0000u); }
; #define EPI_M _Pragma("unroll") for (int m = 0; m < 8; ++m)
; #define EPI_N2 _Pragma("unroll") for (int n2 = 0; n2 < 2; ++n2)
; DI void p6_phase(const Params& p, const float* xin, u16* dst, char* lds) {
;     ...
;       EPI_N2 xq[0][n2] = *(const u32x4*)(xinb + (size_t)EPI_ROW(row0, 0) * D + EPI_COL(col0, 2 * n2));
;       EPI_M {
;         if (m < 7) EPI_N2 xq[(m + 1) & 1][n2] = *(const u32x4*)(xinb + (size_t)EPI_ROW(row0, m + 1) * D + EPI_COL(col0, 2 * n2));
;         EPI_N2 {
;           const u32x4 r = xq[m & 1][n2];
;           const f32x4 xa = {bflo(r[0]), bfhi(r[0]), bflo(r[1]), bfhi(r[1])}, xc = {bflo(r[2]), bfhi(r[2]), bflo(r[3]), bfhi(r[3])};
;           const f32x4 ya = xa * DN_ALPHA + ACC(m, 2 * n2), yc = xc * DN_ALPHA + ACC(m, 2 * n2 + 1);
;           u32x4 yo; yo[0] = pk_f16(ya[0], ya[1]); yo[1] = pk_f16(ya[2], ya[3]); yo[2] = pk_f16(yc[0], yc[1]); yo[3] = pk_f16(yc[2], yc[3]);
;           *(u32x4*)(dst + (size_t)EPI_ROW(row0, m) * D + EPI_COL(col0, 2 * n2)) = yo;
;         }
;         __builtin_amdgcn_sched_barrier(0);
;       }
;     }
	v_mov_b32_e32 v48, v206
	v_mov_b32_e32 v49, v207
	v_mov_b32_e32 v50, v208
	v_mov_b32_e32 v51, v209
	v_lshlrev_b32_e32 v44, 16, v48
	v_and_b32_e32 v45, 0xffff0000, v48
	v_lshlrev_b32_e32 v46, 16, v49
	v_and_b32_e32 v47, 0xffff0000, v49
	v_lshlrev_b32_e32 v48, 16, v50
	v_and_b32_e32 v49, 0xffff0000, v50
	v_lshlrev_b32_e32 v50, 16, v51
	v_and_b32_e32 v51, 0xffff0000, v51
	v_lshl_add_u64 v[42:43], s[8:9], 0, v[56:57]
	v_pk_fma_f32 v[30:31], v[46:47], s[78:79], v[30:31] op_sel_hi:[1,0,1]
	v_pk_fma_f32 v[28:29], v[44:45], s[78:79], v[28:29] op_sel_hi:[1,0,1]
	v_pk_fma_f32 v[44:45], v[50:51], s[78:79], v[26:27] op_sel_hi:[1,0,1]
	v_pk_fma_f32 v[26:27], v[48:49], s[78:79], v[24:25] op_sel_hi:[1,0,1]
	v_cvt_pk_f16_f32 v24, v28, v29
	v_cvt_pk_f16_f32 v25, v30, v31
	v_cvt_pk_f16_f32 v26, v26, v27
	v_cvt_pk_f16_f32 v27, v44, v45
	v_lshl_add_u64 v[28:29], v[42:43], 0, v[134:135]
	global_store_dwordx4 v[28:29], v[24:27], off
	s_waitcnt vmcnt(15)
	v_mov_b32_e32 v52, v210
	v_mov_b32_e32 v53, v211
	v_mov_b32_e32 v54, v212
	v_mov_b32_e32 v55, v213
	v_lshlrev_b32_e32 v30, 16, v54
	v_and_b32_e32 v31, 0xffff0000, v54
	v_lshlrev_b32_e32 v24, 16, v52
	v_and_b32_e32 v25, 0xffff0000, v52
	v_lshlrev_b32_e32 v26, 16, v53
	v_and_b32_e32 v27, 0xffff0000, v53
	v_lshlrev_b32_e32 v42, 16, v55
	v_and_b32_e32 v43, 0xffff0000, v55
	v_pk_fma_f32 v[22:23], v[26:27], s[78:79], v[22:23] op_sel_hi:[1,0,1]
	v_pk_fma_f32 v[20:21], v[24:25], s[78:79], v[20:21] op_sel_hi:[1,0,1]
	v_pk_fma_f32 v[24:25], v[42:43], s[78:79], v[18:19] op_sel_hi:[1,0,1]
	v_pk_fma_f32 v[18:19], v[30:31], s[78:79], v[16:17] op_sel_hi:[1,0,1]
	v_cvt_pk_f16_f32 v16, v20, v21
	v_cvt_pk_f16_f32 v17, v22, v23
	v_cvt_pk_f16_f32 v18, v18, v19
	v_cvt_pk_f16_f32 v19, v24, v25
	global_store_dwordx4 v[28:29], v[16:19], off offset:256
	s_waitcnt vmcnt(15)
	v_mov_b32_e32 v32, v216
	v_mov_b32_e32 v33, v217
	v_mov_b32_e32 v34, v218
	v_mov_b32_e32 v35, v219
	s_nop 0
	v_lshlrev_b32_e32 v18, 16, v32
	v_and_b32_e32 v19, 0xffff0000, v32
	v_lshlrev_b32_e32 v20, 16, v33
	v_and_b32_e32 v21, 0xffff0000, v33
	v_lshlrev_b32_e32 v22, 16, v34
	v_and_b32_e32 v23, 0xffff0000, v34
	v_lshlrev_b32_e32 v24, 16, v35
	v_and_b32_e32 v25, 0xffff0000, v35
	v_lshl_add_u64 v[16:17], s[8:9], 0, v[40:41]
	v_pk_fma_f32 v[14:15], v[20:21], s[78:79], v[14:15] op_sel_hi:[1,0,1]
	v_pk_fma_f32 v[12:13], v[18:19], s[78:79], v[12:13] op_sel_hi:[1,0,1]
	v_pk_fma_f32 v[18:19], v[24:25], s[78:79], v[10:11] op_sel_hi:[1,0,1]
	v_pk_fma_f32 v[10:11], v[22:23], s[78:79], v[8:9] op_sel_hi:[1,0,1]
	v_cvt_pk_f16_f32 v8, v12, v13
	v_cvt_pk_f16_f32 v9, v14, v15
	v_cvt_pk_f16_f32 v10, v10, v11
	v_cvt_pk_f16_f32 v11, v18, v19
	v_lshl_add_u64 v[12:13], v[16:17], 0, v[134:135]
	global_store_dwordx4 v[12:13], v[8:11], off
	s_waitcnt vmcnt(15)
	v_mov_b32_e32 v36, v226
	v_mov_b32_e32 v37, v227
	v_mov_b32_e32 v38, v228
	v_mov_b32_e32 v39, v229
	v_lshlrev_b32_e32 v14, 16, v38
	v_and_b32_e32 v15, 0xffff0000, v38
	v_lshlrev_b32_e32 v8, 16, v36
	v_and_b32_e32 v9, 0xffff0000, v36
	v_lshlrev_b32_e32 v10, 16, v37
	v_and_b32_e32 v11, 0xffff0000, v37
	v_lshlrev_b32_e32 v16, 16, v39
	v_and_b32_e32 v17, 0xffff0000, v39
	v_pk_fma_f32 v[6:7], v[10:11], s[78:79], v[6:7] op_sel_hi:[1,0,1]
	v_pk_fma_f32 v[4:5], v[8:9], s[78:79], v[4:5] op_sel_hi:[1,0,1]
	v_pk_fma_f32 v[8:9], v[16:17], s[78:79], v[2:3] op_sel_hi:[1,0,1]
	v_pk_fma_f32 v[2:3], v[14:15], s[78:79], v[0:1] op_sel_hi:[1,0,1]
	v_cvt_pk_f16_f32 v0, v4, v5
	v_cvt_pk_f16_f32 v1, v6, v7
	v_cvt_pk_f16_f32 v2, v2, v3
	v_cvt_pk_f16_f32 v3, v8, v9
	global_store_dwordx4 v[12:13], v[0:3], off offset:256
	v_readlane_b32 s8, v255, 7
	s_add_i32 s2, s2, s8
	s_cmpk_lt_i32 s2, 0x100
	v_readlane_b32 s9, v255, 8
	s_cbranch_scc0 .LBB0_1056

; DI unsigned pk_f16(float lo, float hi) { f32x2_t v = {lo, hi}; return __builtin_bit_cast(unsigned, __builtin_convertvector(v, f16x2_t)); }
; DI float bflo(unsigned u) { return __uint_as_float(u << 16); }
; DI float bfhi(unsigned u) { return __uint_as_float(u & 0xffff0000u); }
; #define EPI_M _Pragma("unroll") for (int m = 0; m < 8; ++m)
; #define EPI_N2 _Pragma("unroll") for (int n2 = 0; n2 < 2; ++n2)
; DI void p10_phase(const Params& p, int layer, u16* dst, char* lds) {
;     ...
;     EPI_IDX_N
;     {
;       u32x4 xq[2][2];
;       EPI_N2 xq[0][n2] = *(const u32x4*)(x1b + (size_t)EPI_ROW(row0, 0) * D + EPI_COL(col0, 2 * n2));
;       EPI_M {
;         if (m < 7) EPI_N2 xq[(m + 1) & 1][n2] = *(const u32x4*)(x1b + (size_t)EPI_ROW(row0, m + 1) * D + EPI_COL(col0, 2 * n2));
;         EPI_N2 {
;           const u32x4 r = xq[m & 1][n2];
;           const f32x4 xa = {bflo(r[0]), bfhi(r[0]), bflo(r[1]), bfhi(r[1])}, xc = {bflo(r[2]), bfhi(r[2]), bflo(r[3]), bfhi(r[3])};
;           const f32x4 ya = xa * DN_ALPHA + ACC(m, 2 * n2), yc = xc * DN_ALPHA + ACC(m, 2 * n2 + 1);
;           u32x4 yo; yo[0] = pk_f16(ya[0], ya[1]); yo[1] = pk_f16(ya[2], ya[3]); yo[2] = pk_f16(yc[0], yc[1]); yo[3] = pk_f16(yc[2], yc[3]);
;           *(u32x4*)(dst + (size_t)EPI_ROW(row0, m) * D + EPI_COL(col0, 2 * n2)) = yo;
;         }
;         __builtin_amdgcn_sched_barrier(0);
;       }
;     }
.LBB0_1240:
	s_or_b64 exec, exec, s[8:9]
	s_waitcnt vmcnt(0)
	s_barrier
	s_getreg_b32 s2, hwreg(HW_REG_HW_ID, 0, 6)
	s_lshl_b32 s2, s2, 2
	s_and_b32 s2, s2, 0xfc
	s_add_i32 s2, s2, 0x20040
	v_mov_b32_e32 v64, s2
	ds_read_b32 v64, v64
	v_readlane_b32 s8, v254, 20
	v_readlane_b32 s9, v254, 21
	s_waitcnt lgkmcnt(0)
	v_readfirstlane_b32 s2, v64
	s_nop 1
	v_lshl_or_b32 v64, s2, 6, v214
	v_readlane_b32 s2, v254, 12
	v_ashrrev_i32_e32 v122, 2, v64
	v_and_b32_e32 v137, 0xffffffc0, v122
	v_and_b32_e32 v136, 15, v64
	v_add_u32_e32 v122, s36, v137
	v_lshrrev_b32_e32 v64, 1, v64
	v_or_b32_e32 v122, v122, v136
	v_and_b32_e32 v64, 0x78, v64
	v_ashrrev_i32_e32 v123, 31, v122
	v_or_b32_e32 v124, s42, v64
	v_lshlrev_b64 v[122:123], 11, v[122:123]
	v_readlane_b32 s3, v254, 13
	v_ashrrev_i32_e32 v125, 31, v124
	v_lshlrev_b64 v[134:135], 1, v[124:125]
	v_lshl_add_u64 v[122:123], s[2:3], 0, v[122:123]
	v_or_b32_e32 v64, s36, v136
	v_lshl_add_u64 v[122:123], v[122:123], 0, v[134:135]
	v_add_u32_e32 v136, v64, v137
	s_mov_b32 s101, 0
	global_load_dwordx4 v[158:161], v[122:123], off
	global_load_dwordx4 v[162:165], v[122:123], off offset:256
	s_mov_b32 s100, 0x8000
	v_lshl_add_u64 v[224:225], v[122:123], 0, s[100:101]
	global_load_dwordx4 v[166:169], v[224:225], off
	global_load_dwordx4 v[170:173], v[224:225], off offset:256
	s_mov_b32 s100, 0x10000
	v_lshl_add_u64 v[224:225], v[122:123], 0, s[100:101]
	global_load_dwordx4 v[174:177], v[224:225], off
	global_load_dwordx4 v[178:181], v[224:225], off offset:256
	s_mov_b32 s100, 0x18000
	v_lshl_add_u64 v[224:225], v[122:123], 0, s[100:101]
	global_load_dwordx4 v[182:185], v[224:225], off
	global_load_dwordx4 v[186:189], v[224:225], off offset:256
	s_mov_b32 s100, 0x40000
	v_lshl_add_u64 v[224:225], v[122:123], 0, s[100:101]
	global_load_dwordx4 v[190:193], v[224:225], off
	global_load_dwordx4 v[194:197], v[224:225], off offset:256
	s_mov_b32 s100, 0x48000
	v_lshl_add_u64 v[224:225], v[122:123], 0, s[100:101]
	global_load_dwordx4 v[198:201], v[224:225], off
	global_load_dwordx4 v[202:205], v[224:225], off offset:256
	s_mov_b32 s100, 0x50000
	v_lshl_add_u64 v[224:225], v[122:123], 0, s[100:101]
	global_load_dwordx4 v[206:209], v[224:225], off
	global_load_dwordx4 v[210:213], v[224:225], off offset:256
	s_mov_b32 s100, 0x58000
	v_lshl_add_u64 v[224:225], v[122:123], 0, s[100:101]
	global_load_dwordx4 v[216:219], v[224:225], off
	global_load_dwordx4 v[226:229], v[224:225], off offset:256
	v_or_b32_e32 v122, 16, v136
	v_ashrrev_i32_e32 v123, 31, v122
	v_lshlrev_b64 v[150:151], 11, v[122:123]
	v_lshl_add_u64 v[122:123], s[2:3], 0, v[150:151]
	v_lshl_add_u64 v[122:123], v[122:123], 0, v[134:135]
	s_nop 0
	v_ashrrev_i32_e32 v137, 31, v136
	v_lshlrev_b64 v[152:153], 11, v[136:137]
	v_lshl_add_u64 v[152:153], s[8:9], 0, v[152:153]
	s_waitcnt vmcnt(15)
	v_mov_b32_e32 v138, v158
	v_mov_b32_e32 v139, v159
	v_mov_b32_e32 v140, v160
	v_mov_b32_e32 v141, v161
	v_lshlrev_b32_e32 v154, 16, v138
	v_and_b32_e32 v155, 0xffff0000, v138
	v_lshlrev_b32_e32 v138, 16, v139
	v_and_b32_e32 v139, 0xffff0000, v139
	v_lshlrev_b32_e32 v156, 16, v140
	v_and_b32_e32 v157, 0xffff0000, v140
	v_lshlrev_b32_e32 v140, 16, v141
	v_and_b32_e32 v141, 0xffff0000, v141
	v_pk_fma_f32 v[128:129], v[138:139], s[78:79], v[128:129] op_sel_hi:[1,0,1]
	v_pk_fma_f32 v[126:127], v[154:155], s[78:79], v[126:127] op_sel_hi:[1,0,1]
	v_pk_fma_f32 v[132:133], v[140:141], s[78:79], v[132:133] op_sel_hi:[1,0,1]
	v_pk_fma_f32 v[130:131], v[156:157], s[78:79], v[130:131] op_sel_hi:[1,0,1]
	v_cvt_pk_f16_f32 v126, v126, v127
	v_cvt_pk_f16_f32 v127, v128, v129
	v_cvt_pk_f16_f32 v128, v130, v131
	v_cvt_pk_f16_f32 v129, v132, v133
	v_lshl_add_u64 v[130:131], v[152:153], 0, v[134:135]
	global_store_dwordx4 v[130:131], v[126:129], off
	s_waitcnt vmcnt(15)
	v_mov_b32_e32 v142, v162
	v_mov_b32_e32 v143, v163
	v_mov_b32_e32 v144, v164
	v_mov_b32_e32 v145, v165
	v_lshlrev_b32_e32 v132, 16, v144
	v_and_b32_e32 v133, 0xffff0000, v144
	v_lshlrev_b32_e32 v126, 16, v142
	v_and_b32_e32 v127, 0xffff0000, v142
	v_lshlrev_b32_e32 v128, 16, v143
	v_and_b32_e32 v129, 0xffff0000, v143
	v_lshlrev_b32_e32 v138, 16, v145
	v_and_b32_e32 v139, 0xffff0000, v145
	v_pk_fma_f32 v[120:121], v[128:129], s[78:79], v[120:121] op_sel_hi:[1,0,1]
	v_pk_fma_f32 v[118:119], v[126:127], s[78:79], v[118:119] op_sel_hi:[1,0,1]
	v_pk_fma_f32 v[126:127], v[138:139], s[78:79], v[116:117] op_sel_hi:[1,0,1]
	v_pk_fma_f32 v[116:117], v[132:133], s[78:79], v[114:115] op_sel_hi:[1,0,1]
	v_cvt_pk_f16_f32 v114, v118, v119
	v_cvt_pk_f16_f32 v115, v120, v121
	v_cvt_pk_f16_f32 v116, v116, v117
	v_cvt_pk_f16_f32 v117, v126, v127
	global_store_dwordx4 v[130:131], v[114:117], off offset:256
	s_nop 1
	v_or_b32_e32 v114, 32, v136
	v_ashrrev_i32_e32 v115, 31, v114
	v_lshlrev_b64 v[126:127], 11, v[114:115]
	v_lshl_add_u64 v[114:115], s[2:3], 0, v[126:127]
	v_lshl_add_u64 v[118:119], v[114:115], 0, v[134:135]
	s_nop 0
	s_waitcnt vmcnt(15)
	v_mov_b32_e32 v146, v166
	v_mov_b32_e32 v147, v167
	v_mov_b32_e32 v148, v168
	v_mov_b32_e32 v149, v169
	v_lshlrev_b32_e32 v130, 16, v146
	v_and_b32_e32 v131, 0xffff0000, v146
	v_lshlrev_b32_e32 v132, 16, v147
	v_and_b32_e32 v133, 0xffff0000, v147
	v_lshlrev_b32_e32 v138, 16, v148
	v_and_b32_e32 v139, 0xffff0000, v148
	v_lshlrev_b32_e32 v140, 16, v149
	v_and_b32_e32 v141, 0xffff0000, v149
	v_lshl_add_u64 v[128:129], s[8:9], 0, v[150:151]
	v_pk_fma_f32 v[112:113], v[132:133], s[78:79], v[112:113] op_sel_hi:[1,0,1]
	v_pk_fma_f32 v[110:111], v[130:131], s[78:79], v[110:111] op_sel_hi:[1,0,1]
	v_pk_fma_f32 v[130:131], v[140:141], s[78:79], v[108:109] op_sel_hi:[1,0,1]
	v_pk_fma_f32 v[108:109], v[138:139], s[78:79], v[106:107] op_sel_hi:[1,0,1]
	v_cvt_pk_f16_f32 v106, v110, v111
	v_cvt_pk_f16_f32 v107, v112, v113
	v_cvt_pk_f16_f32 v108, v108, v109
	v_cvt_pk_f16_f32 v109, v130, v131
	v_lshl_add_u64 v[110:111], v[128:129], 0, v[134:135]
	global_store_dwordx4 v[110:111], v[106:109], off
	s_waitcnt vmcnt(15)
; DI unsigned pk_f16(float lo, float hi) { f32x2_t v = {lo, hi}; return __builtin_bit_cast(unsigned, __builtin_convertvector(v, f16x2_t)); }
; DI float bflo(unsigned u) { return __uint_as_float(u << 16); }
; DI float bfhi(unsigned u) { return __uint_as_float(u & 0xffff0000u); }
; #define EPI_M _Pragma("unroll") for (int m = 0; m < 8; ++m)
; #define EPI_N2 _Pragma("unroll") for (int n2 = 0; n2 < 2; ++n2)
; DI void p10_phase(const Params& p, int layer, u16* dst, char* lds) {
;     ...
;       EPI_N2 xq[0][n2] = *(const u32x4*)(x1b + (size_t)EPI_ROW(row0, 0) * D + EPI_COL(col0, 2 * n2));
;       EPI_M {
;         if (m < 7) EPI_N2 xq[(m + 1) & 1][n2] = *(const u32x4*)(x1b + (size_t)EPI_ROW(row0, m + 1) * D + EPI_COL(col0, 2 * n2));
;         EPI_N2 {
;           const u32x4 r = xq[m & 1][n2];
;           const f32x4 xa = {bflo(r[0]), bfhi(r[0]), bflo(r[1]), bfhi(r[1])}, xc = {bflo(r[2]), bfhi(r[2]), bflo(r[3]), bfhi(r[3])};
;           const f32x4 ya = xa * DN_ALPHA + ACC(m, 2 * n2), yc = xc * DN_ALPHA + ACC(m, 2 * n2 + 1);
;           u32x4 yo; yo[0] = pk_f16(ya[0], ya[1]); yo[1] = pk_f16(ya[2], ya[3]); yo[2] = pk_f16(yc[0], yc[1]); yo[3] = pk_f16(yc[2], yc[3]);
;           *(u32x4*)(dst + (size_t)EPI_ROW(row0, m) * D + EPI_COL(col0, 2 * n2)) = yo;
;         }
;         __builtin_amdgcn_sched_barrier(0);
;       }
	v_mov_b32_e32 v122, v170
	v_mov_b32_e32 v123, v171
	v_mov_b32_e32 v124, v172
	v_mov_b32_e32 v125, v173
	v_lshlrev_b32_e32 v112, 16, v124
	v_and_b32_e32 v113, 0xffff0000, v124
	v_lshlrev_b32_e32 v106, 16, v122
	v_and_b32_e32 v107, 0xffff0000, v122
	v_lshlrev_b32_e32 v108, 16, v123
	v_and_b32_e32 v109, 0xffff0000, v123
	v_lshlrev_b32_e32 v122, 16, v125
	v_and_b32_e32 v123, 0xffff0000, v125
	v_pk_fma_f32 v[104:105], v[108:109], s[78:79], v[104:105] op_sel_hi:[1,0,1]
	v_pk_fma_f32 v[102:103], v[106:107], s[78:79], v[102:103] op_sel_hi:[1,0,1]
	v_pk_fma_f32 v[106:107], v[122:123], s[78:79], v[100:101] op_sel_hi:[1,0,1]
	v_pk_fma_f32 v[100:101], v[112:113], s[78:79], v[98:99] op_sel_hi:[1,0,1]
	v_cvt_pk_f16_f32 v98, v102, v103
	v_cvt_pk_f16_f32 v99, v104, v105
	v_cvt_pk_f16_f32 v100, v100, v101
	v_cvt_pk_f16_f32 v101, v106, v107
	global_store_dwordx4 v[110:111], v[98:101], off offset:256
	s_nop 1
	v_or_b32_e32 v98, 48, v136
	v_ashrrev_i32_e32 v99, 31, v98
	v_lshlrev_b64 v[106:107], 11, v[98:99]
	v_lshl_add_u64 v[98:99], s[2:3], 0, v[106:107]
	v_lshl_add_u64 v[102:103], v[98:99], 0, v[134:135]
	s_nop 0
	s_waitcnt vmcnt(15)
	v_mov_b32_e32 v114, v174
	v_mov_b32_e32 v115, v175
	v_mov_b32_e32 v116, v176
	v_mov_b32_e32 v117, v177
	v_lshlrev_b32_e32 v110, 16, v114
	v_and_b32_e32 v111, 0xffff0000, v114
	v_lshlrev_b32_e32 v112, 16, v115
	v_and_b32_e32 v113, 0xffff0000, v115
	v_lshlrev_b32_e32 v114, 16, v116
	v_and_b32_e32 v115, 0xffff0000, v116
	v_lshlrev_b32_e32 v116, 16, v117
	v_and_b32_e32 v117, 0xffff0000, v117
	v_lshl_add_u64 v[108:109], s[8:9], 0, v[126:127]
	v_pk_fma_f32 v[96:97], v[112:113], s[78:79], v[96:97] op_sel_hi:[1,0,1]
	v_pk_fma_f32 v[94:95], v[110:111], s[78:79], v[94:95] op_sel_hi:[1,0,1]
	v_pk_fma_f32 v[110:111], v[116:117], s[78:79], v[92:93] op_sel_hi:[1,0,1]
	v_pk_fma_f32 v[92:93], v[114:115], s[78:79], v[90:91] op_sel_hi:[1,0,1]
	v_cvt_pk_f16_f32 v90, v94, v95
	v_cvt_pk_f16_f32 v91, v96, v97
	v_cvt_pk_f16_f32 v92, v92, v93
	v_cvt_pk_f16_f32 v93, v110, v111
	v_lshl_add_u64 v[94:95], v[108:109], 0, v[134:135]
	global_store_dwordx4 v[94:95], v[90:93], off
	s_waitcnt vmcnt(15)
	v_mov_b32_e32 v118, v178
	v_mov_b32_e32 v119, v179
	v_mov_b32_e32 v120, v180
	v_mov_b32_e32 v121, v181
	v_lshlrev_b32_e32 v96, 16, v120
	v_and_b32_e32 v97, 0xffff0000, v120
	v_lshlrev_b32_e32 v90, 16, v118
	v_and_b32_e32 v91, 0xffff0000, v118
	v_lshlrev_b32_e32 v92, 16, v119
	v_and_b32_e32 v93, 0xffff0000, v119
	v_lshlrev_b32_e32 v108, 16, v121
	v_and_b32_e32 v109, 0xffff0000, v121
	v_pk_fma_f32 v[88:89], v[92:93], s[78:79], v[88:89] op_sel_hi:[1,0,1]
	v_pk_fma_f32 v[86:87], v[90:91], s[78:79], v[86:87] op_sel_hi:[1,0,1]
	v_pk_fma_f32 v[90:91], v[108:109], s[78:79], v[84:85] op_sel_hi:[1,0,1]
	v_pk_fma_f32 v[84:85], v[96:97], s[78:79], v[82:83] op_sel_hi:[1,0,1]
	v_cvt_pk_f16_f32 v82, v86, v87
	v_cvt_pk_f16_f32 v83, v88, v89
	v_cvt_pk_f16_f32 v84, v84, v85
	v_cvt_pk_f16_f32 v85, v90, v91
	global_store_dwordx4 v[94:95], v[82:85], off offset:256
	s_nop 1
	v_add_u32_e32 v82, 0x80, v136
	v_ashrrev_i32_e32 v83, 31, v82
	v_lshlrev_b64 v[90:91], 11, v[82:83]
	v_lshl_add_u64 v[82:83], s[2:3], 0, v[90:91]
	v_lshl_add_u64 v[86:87], v[82:83], 0, v[134:135]
	s_nop 0
	s_waitcnt vmcnt(15)
	v_mov_b32_e32 v98, v182
	v_mov_b32_e32 v99, v183
	v_mov_b32_e32 v100, v184
	v_mov_b32_e32 v101, v185
	v_lshlrev_b32_e32 v94, 16, v98
	v_and_b32_e32 v95, 0xffff0000, v98
	v_lshlrev_b32_e32 v96, 16, v99
	v_and_b32_e32 v97, 0xffff0000, v99
	v_lshlrev_b32_e32 v98, 16, v100
	v_and_b32_e32 v99, 0xffff0000, v100
	v_lshlrev_b32_e32 v100, 16, v101
	v_and_b32_e32 v101, 0xffff0000, v101
	v_lshl_add_u64 v[92:93], s[8:9], 0, v[106:107]
	v_pk_fma_f32 v[80:81], v[96:97], s[78:79], v[80:81] op_sel_hi:[1,0,1]
	v_pk_fma_f32 v[78:79], v[94:95], s[78:79], v[78:79] op_sel_hi:[1,0,1]
	v_pk_fma_f32 v[94:95], v[100:101], s[78:79], v[76:77] op_sel_hi:[1,0,1]
	v_pk_fma_f32 v[76:77], v[98:99], s[78:79], v[74:75] op_sel_hi:[1,0,1]
	v_cvt_pk_f16_f32 v74, v78, v79
	v_cvt_pk_f16_f32 v75, v80, v81
	v_cvt_pk_f16_f32 v76, v76, v77
	v_cvt_pk_f16_f32 v77, v94, v95
	v_lshl_add_u64 v[78:79], v[92:93], 0, v[134:135]
	global_store_dwordx4 v[78:79], v[74:77], off
	s_waitcnt vmcnt(15)
	v_mov_b32_e32 v102, v186
	v_mov_b32_e32 v103, v187
	v_mov_b32_e32 v104, v188
	v_mov_b32_e32 v105, v189
	v_lshlrev_b32_e32 v80, 16, v104
	v_and_b32_e32 v81, 0xffff0000, v104
	v_lshlrev_b32_e32 v74, 16, v102
	v_and_b32_e32 v75, 0xffff0000, v102
	v_lshlrev_b32_e32 v76, 16, v103
	v_and_b32_e32 v77, 0xffff0000, v103
	v_lshlrev_b32_e32 v92, 16, v105
	v_and_b32_e32 v93, 0xffff0000, v105
	v_pk_fma_f32 v[72:73], v[76:77], s[78:79], v[72:73] op_sel_hi:[1,0,1]
	v_pk_fma_f32 v[70:71], v[74:75], s[78:79], v[70:71] op_sel_hi:[1,0,1]
	v_pk_fma_f32 v[74:75], v[92:93], s[78:79], v[68:69] op_sel_hi:[1,0,1]
	v_pk_fma_f32 v[68:69], v[80:81], s[78:79], v[66:67] op_sel_hi:[1,0,1]
	v_cvt_pk_f16_f32 v66, v70, v71
	v_cvt_pk_f16_f32 v67, v72, v73
	v_cvt_pk_f16_f32 v68, v68, v69
	v_cvt_pk_f16_f32 v69, v74, v75
	global_store_dwordx4 v[78:79], v[66:69], off offset:256
	s_nop 1
	v_add_u32_e32 v66, 0x90, v136
	v_ashrrev_i32_e32 v67, 31, v66
	v_lshlrev_b64 v[74:75], 11, v[66:67]
	v_lshl_add_u64 v[66:67], s[2:3], 0, v[74:75]
	v_lshl_add_u64 v[70:71], v[66:67], 0, v[134:135]
	s_nop 0
	s_waitcnt vmcnt(15)
; DI unsigned pk_f16(float lo, float hi) { f32x2_t v = {lo, hi}; return __builtin_bit_cast(unsigned, __builtin_convertvector(v, f16x2_t)); }
; DI float bflo(unsigned u) { return __uint_as_float(u << 16); }
; DI float bfhi(unsigned u) { return __uint_as_float(u & 0xffff0000u); }
; #define EPI_M _Pragma("unroll") for (int m = 0; m < 8; ++m)
; #define EPI_N2 _Pragma("unroll") for (int n2 = 0; n2 < 2; ++n2)
; DI void p10_phase(const Params& p, int layer, u16* dst, char* lds) {
;     ...
;       EPI_N2 xq[0][n2] = *(const u32x4*)(x1b + (size_t)EPI_ROW(row0, 0) * D + EPI_COL(col0, 2 * n2));
;       EPI_M {
;         if (m < 7) EPI_N2 xq[(m + 1) & 1][n2] = *(const u32x4*)(x1b + (size_t)EPI_ROW(row0, m + 1) * D + EPI_COL(col0, 2 * n2));
;         EPI_N2 {
;           const u32x4 r = xq[m & 1][n2];
;           const f32x4 xa = {bflo(r[0]), bfhi(r[0]), bflo(r[1]), bfhi(r[1])}, xc = {bflo(r[2]), bfhi(r[2]), bflo(r[3]), bfhi(r[3])};
;           const f32x4 ya = xa * DN_ALPHA + ACC(m, 2 * n2), yc = xc * DN_ALPHA + ACC(m, 2 * n2 + 1);
;           u32x4 yo; yo[0] = pk_f16(ya[0], ya[1]); yo[1] = pk_f16(ya[2], ya[3]); yo[2] = pk_f16(yc[0], yc[1]); yo[3] = pk_f16(yc[2], yc[3]);
;           *(u32x4*)(dst + (size_t)EPI_ROW(row0, m) * D + EPI_COL(col0, 2 * n2)) = yo;
;         }
;         __builtin_amdgcn_sched_barrier(0);
;       }
	v_mov_b32_e32 v82, v190
	v_mov_b32_e32 v83, v191
	v_mov_b32_e32 v84, v192
	v_mov_b32_e32 v85, v193
	v_lshlrev_b32_e32 v78, 16, v82
	v_and_b32_e32 v79, 0xffff0000, v82
	v_lshlrev_b32_e32 v80, 16, v83
	v_and_b32_e32 v81, 0xffff0000, v83
	v_lshlrev_b32_e32 v82, 16, v84
	v_and_b32_e32 v83, 0xffff0000, v84
	v_lshlrev_b32_e32 v84, 16, v85
	v_and_b32_e32 v85, 0xffff0000, v85
	v_lshl_add_u64 v[76:77], s[8:9], 0, v[90:91]
	v_pk_fma_f32 v[62:63], v[80:81], s[78:79], v[62:63] op_sel_hi:[1,0,1]
	v_pk_fma_f32 v[60:61], v[78:79], s[78:79], v[60:61] op_sel_hi:[1,0,1]
	v_pk_fma_f32 v[78:79], v[84:85], s[78:79], v[58:59] op_sel_hi:[1,0,1]
	v_pk_fma_f32 v[58:59], v[82:83], s[78:79], v[56:57] op_sel_hi:[1,0,1]
	v_cvt_pk_f16_f32 v56, v60, v61
	v_cvt_pk_f16_f32 v57, v62, v63
	v_cvt_pk_f16_f32 v58, v58, v59
	v_cvt_pk_f16_f32 v59, v78, v79
	v_lshl_add_u64 v[60:61], v[76:77], 0, v[134:135]
	global_store_dwordx4 v[60:61], v[56:59], off
	s_waitcnt vmcnt(15)
	v_mov_b32_e32 v86, v194
	v_mov_b32_e32 v87, v195
	v_mov_b32_e32 v88, v196
	v_mov_b32_e32 v89, v197
	v_lshlrev_b32_e32 v62, 16, v88
	v_and_b32_e32 v63, 0xffff0000, v88
	v_lshlrev_b32_e32 v56, 16, v86
	v_and_b32_e32 v57, 0xffff0000, v86
	v_lshlrev_b32_e32 v58, 16, v87
	v_and_b32_e32 v59, 0xffff0000, v87
	v_lshlrev_b32_e32 v76, 16, v89
	v_and_b32_e32 v77, 0xffff0000, v89
	v_pk_fma_f32 v[54:55], v[58:59], s[78:79], v[54:55] op_sel_hi:[1,0,1]
	v_pk_fma_f32 v[52:53], v[56:57], s[78:79], v[52:53] op_sel_hi:[1,0,1]
	v_pk_fma_f32 v[56:57], v[76:77], s[78:79], v[50:51] op_sel_hi:[1,0,1]
	v_pk_fma_f32 v[50:51], v[62:63], s[78:79], v[48:49] op_sel_hi:[1,0,1]
	v_cvt_pk_f16_f32 v48, v52, v53
	v_cvt_pk_f16_f32 v49, v54, v55
	v_cvt_pk_f16_f32 v50, v50, v51
	v_cvt_pk_f16_f32 v51, v56, v57
	global_store_dwordx4 v[60:61], v[48:51], off offset:256
	s_nop 1
	v_add_u32_e32 v48, 0xa0, v136
	v_ashrrev_i32_e32 v49, 31, v48
	v_lshlrev_b64 v[56:57], 11, v[48:49]
	v_lshl_add_u64 v[48:49], s[2:3], 0, v[56:57]
	v_lshl_add_u64 v[52:53], v[48:49], 0, v[134:135]
	s_nop 0
	s_waitcnt vmcnt(15)
	v_mov_b32_e32 v66, v198
	v_mov_b32_e32 v67, v199
	v_mov_b32_e32 v68, v200
	v_mov_b32_e32 v69, v201
	v_lshlrev_b32_e32 v60, 16, v66
	v_and_b32_e32 v61, 0xffff0000, v66
	v_lshlrev_b32_e32 v62, 16, v67
	v_and_b32_e32 v63, 0xffff0000, v67
	v_lshlrev_b32_e32 v66, 16, v68
	v_and_b32_e32 v67, 0xffff0000, v68
	v_lshlrev_b32_e32 v68, 16, v69
	v_and_b32_e32 v69, 0xffff0000, v69
	v_lshl_add_u64 v[58:59], s[8:9], 0, v[74:75]
	v_pk_fma_f32 v[46:47], v[62:63], s[78:79], v[46:47] op_sel_hi:[1,0,1]
	v_pk_fma_f32 v[44:45], v[60:61], s[78:79], v[44:45] op_sel_hi:[1,0,1]
	v_pk_fma_f32 v[60:61], v[68:69], s[78:79], v[42:43] op_sel_hi:[1,0,1]
	v_pk_fma_f32 v[42:43], v[66:67], s[78:79], v[40:41] op_sel_hi:[1,0,1]
	v_cvt_pk_f16_f32 v40, v44, v45
	v_cvt_pk_f16_f32 v41, v46, v47
	v_cvt_pk_f16_f32 v42, v42, v43
	v_cvt_pk_f16_f32 v43, v60, v61
	v_lshl_add_u64 v[44:45], v[58:59], 0, v[134:135]
	global_store_dwordx4 v[44:45], v[40:43], off
	s_waitcnt vmcnt(15)
	v_mov_b32_e32 v70, v202
	v_mov_b32_e32 v71, v203
	v_mov_b32_e32 v72, v204
	v_mov_b32_e32 v73, v205
	v_lshlrev_b32_e32 v46, 16, v72
	v_and_b32_e32 v47, 0xffff0000, v72
	v_lshlrev_b32_e32 v40, 16, v70
	v_and_b32_e32 v41, 0xffff0000, v70
	v_lshlrev_b32_e32 v42, 16, v71
	v_and_b32_e32 v43, 0xffff0000, v71
	v_lshlrev_b32_e32 v58, 16, v73
	v_and_b32_e32 v59, 0xffff0000, v73
	v_pk_fma_f32 v[38:39], v[42:43], s[78:79], v[38:39] op_sel_hi:[1,0,1]
	v_pk_fma_f32 v[36:37], v[40:41], s[78:79], v[36:37] op_sel_hi:[1,0,1]
	v_pk_fma_f32 v[40:41], v[58:59], s[78:79], v[34:35] op_sel_hi:[1,0,1]
	v_pk_fma_f32 v[34:35], v[46:47], s[78:79], v[32:33] op_sel_hi:[1,0,1]
	v_cvt_pk_f16_f32 v32, v36, v37
	v_cvt_pk_f16_f32 v33, v38, v39
	v_cvt_pk_f16_f32 v34, v34, v35
	v_cvt_pk_f16_f32 v35, v40, v41
	global_store_dwordx4 v[44:45], v[32:35], off offset:256
	s_nop 1
	v_add_u32_e32 v32, 0xb0, v136
	v_ashrrev_i32_e32 v33, 31, v32
	v_lshlrev_b64 v[40:41], 11, v[32:33]
	v_lshl_add_u64 v[32:33], s[2:3], 0, v[40:41]
	v_lshl_add_u64 v[36:37], v[32:33], 0, v[134:135]
	s_nop 0
	s_waitcnt vmcnt(15)
; DI unsigned pk_f16(float lo, float hi) { f32x2_t v = {lo, hi}; return __builtin_bit_cast(unsigned, __builtin_convertvector(v, f16x2_t)); }
; DI float bflo(unsigned u) { return __uint_as_float(u << 16); }
; DI float bfhi(unsigned u) { return __uint_as_float(u & 0xffff0000u); }
; #define EPI_M _Pragma("unroll") for (int m = 0; m < 8; ++m)
; #define EPI_N2 _Pragma("unroll") for (int n2 = 0; n2 < 2; ++n2)
; DI void p10_phase(const Params& p, int layer, u16* dst, char* lds) {
;     ...
;   for (int tile = blockIdx.x; tile < 64 * 4; tile += gridDim.x) {
;     ...
;       EPI_N2 xq[0][n2] = *(const u32x4*)(x1b + (size_t)EPI_ROW(row0, 0) * D + EPI_COL(col0, 2 * n2));
;       EPI_M {
;         if (m < 7) EPI_N2 xq[(m + 1) & 1][n2] = *(const u32x4*)(x1b + (size_t)EPI_ROW(row0, m + 1) * D + EPI_COL(col0, 2 * n2));
;         EPI_N2 {
;           const u32x4 r = xq[m & 1][n2];
;           const f32x4 xa = {bflo(r[0]), bfhi(r[0]), bflo(r[1]), bfhi(r[1])}, xc = {bflo(r[2]), bfhi(r[2]), bflo(r[3]), bfhi(r[3])};
;           const f32x4 ya = xa * DN_ALPHA + ACC(m, 2 * n2), yc = xc * DN_ALPHA + ACC(m, 2 * n2 + 1);
;           u32x4 yo; yo[0] = pk_f16(ya[0], ya[1]); yo[1] = pk_f16(ya[2], ya[3]); yo[2] = pk_f16(yc[0], yc[1]); yo[3] = pk_f16(yc[2], yc[3]);
;           *(u32x4*)(dst + (size_t)EPI_ROW(row0, m) * D + EPI_COL(col0, 2 * n2)) = yo;
;         }
;         __builtin_amdgcn_sched_barrier(0);
;       }
;     }
	v_mov_b32_e32 v48, v206
	v_mov_b32_e32 v49, v207
	v_mov_b32_e32 v50, v208
	v_mov_b32_e32 v51, v209
	v_lshlrev_b32_e32 v44, 16, v48
	v_and_b32_e32 v45, 0xffff0000, v48
	v_lshlrev_b32_e32 v46, 16, v49
	v_and_b32_e32 v47, 0xffff0000, v49
	v_lshlrev_b32_e32 v48, 16, v50
	v_and_b32_e32 v49, 0xffff0000, v50
	v_lshlrev_b32_e32 v50, 16, v51
	v_and_b32_e32 v51, 0xffff0000, v51
	v_lshl_add_u64 v[42:43], s[8:9], 0, v[56:57]
	v_pk_fma_f32 v[30:31], v[46:47], s[78:79], v[30:31] op_sel_hi:[1,0,1]
	v_pk_fma_f32 v[28:29], v[44:45], s[78:79], v[28:29] op_sel_hi:[1,0,1]
	v_pk_fma_f32 v[44:45], v[50:51], s[78:79], v[26:27] op_sel_hi:[1,0,1]
	v_pk_fma_f32 v[26:27], v[48:49], s[78:79], v[24:25] op_sel_hi:[1,0,1]
	v_cvt_pk_f16_f32 v24, v28, v29
	v_cvt_pk_f16_f32 v25, v30, v31
	v_cvt_pk_f16_f32 v26, v26, v27
	v_cvt_pk_f16_f32 v27, v44, v45
	v_lshl_add_u64 v[28:29], v[42:43], 0, v[134:135]
	global_store_dwordx4 v[28:29], v[24:27], off
	s_waitcnt vmcnt(15)
	v_mov_b32_e32 v52, v210
	v_mov_b32_e32 v53, v211
	v_mov_b32_e32 v54, v212
	v_mov_b32_e32 v55, v213
	v_lshlrev_b32_e32 v30, 16, v54
	v_and_b32_e32 v31, 0xffff0000, v54
	v_lshlrev_b32_e32 v24, 16, v52
	v_and_b32_e32 v25, 0xffff0000, v52
	v_lshlrev_b32_e32 v26, 16, v53
	v_and_b32_e32 v27, 0xffff0000, v53
	v_lshlrev_b32_e32 v42, 16, v55
	v_and_b32_e32 v43, 0xffff0000, v55
	v_pk_fma_f32 v[22:23], v[26:27], s[78:79], v[22:23] op_sel_hi:[1,0,1]
	v_pk_fma_f32 v[20:21], v[24:25], s[78:79], v[20:21] op_sel_hi:[1,0,1]
	v_pk_fma_f32 v[24:25], v[42:43], s[78:79], v[18:19] op_sel_hi:[1,0,1]
	v_pk_fma_f32 v[18:19], v[30:31], s[78:79], v[16:17] op_sel_hi:[1,0,1]
	v_cvt_pk_f16_f32 v16, v20, v21
	v_cvt_pk_f16_f32 v17, v22, v23
	v_cvt_pk_f16_f32 v18, v18, v19
	v_cvt_pk_f16_f32 v19, v24, v25
	global_store_dwordx4 v[28:29], v[16:19], off offset:256
	s_waitcnt vmcnt(15)
	v_mov_b32_e32 v32, v216
	v_mov_b32_e32 v33, v217
	v_mov_b32_e32 v34, v218
	v_mov_b32_e32 v35, v219
	s_nop 0
	v_lshlrev_b32_e32 v18, 16, v32
	v_and_b32_e32 v19, 0xffff0000, v32
	v_lshlrev_b32_e32 v20, 16, v33
	v_and_b32_e32 v21, 0xffff0000, v33
	v_lshlrev_b32_e32 v22, 16, v34
	v_and_b32_e32 v23, 0xffff0000, v34
	v_lshlrev_b32_e32 v24, 16, v35
	v_and_b32_e32 v25, 0xffff0000, v35
	v_lshl_add_u64 v[16:17], s[8:9], 0, v[40:41]
	v_pk_fma_f32 v[14:15], v[20:21], s[78:79], v[14:15] op_sel_hi:[1,0,1]
	v_pk_fma_f32 v[12:13], v[18:19], s[78:79], v[12:13] op_sel_hi:[1,0,1]
	v_pk_fma_f32 v[18:19], v[24:25], s[78:79], v[10:11] op_sel_hi:[1,0,1]
	v_pk_fma_f32 v[10:11], v[22:23], s[78:79], v[8:9] op_sel_hi:[1,0,1]
	v_cvt_pk_f16_f32 v8, v12, v13
	v_cvt_pk_f16_f32 v9, v14, v15
	v_cvt_pk_f16_f32 v10, v10, v11
	v_cvt_pk_f16_f32 v11, v18, v19
	v_lshl_add_u64 v[12:13], v[16:17], 0, v[134:135]
	global_store_dwordx4 v[12:13], v[8:11], off
	s_waitcnt vmcnt(15)
	v_mov_b32_e32 v36, v226
	v_mov_b32_e32 v37, v227
	v_mov_b32_e32 v38, v228
	v_mov_b32_e32 v39, v229
	v_lshlrev_b32_e32 v14, 16, v38
	v_and_b32_e32 v15, 0xffff0000, v38
	v_lshlrev_b32_e32 v8, 16, v36
	v_and_b32_e32 v9, 0xffff0000, v36
	v_lshlrev_b32_e32 v10, 16, v37
	v_and_b32_e32 v11, 0xffff0000, v37
	v_lshlrev_b32_e32 v16, 16, v39
	v_and_b32_e32 v17, 0xffff0000, v39
	v_pk_fma_f32 v[6:7], v[10:11], s[78:79], v[6:7] op_sel_hi:[1,0,1]
	v_pk_fma_f32 v[4:5], v[8:9], s[78:79], v[4:5] op_sel_hi:[1,0,1]
	v_pk_fma_f32 v[8:9], v[16:17], s[78:79], v[2:3] op_sel_hi:[1,0,1]
	v_pk_fma_f32 v[2:3], v[14:15], s[78:79], v[0:1] op_sel_hi:[1,0,1]
	v_cvt_pk_f16_f32 v0, v4, v5
	v_cvt_pk_f16_f32 v1, v6, v7
	v_cvt_pk_f16_f32 v2, v2, v3
	v_cvt_pk_f16_f32 v3, v8, v9
	global_store_dwordx4 v[12:13], v[0:3], off offset:256
	v_readlane_b32 s2, v255, 7
	s_add_i32 s50, s50, s2
	s_cmpk_lt_i32 s50, 0x100
	v_readlane_b32 s3, v255, 8
	s_cbranch_scc0 .LBB0_1269
